# LDS-DMA issue in the GEMM loops: address add moved behind the m0 write (serves as the wait state), s_nop 0 dropped (30 sites)
# speedup vs baseline: 1.0004x; 1.0004x over previous
; #define PG8_STAGE(bufoff, gbase, voff) do { _Pragma("unroll") for (int _i = 0; _i < 2; ++_i) \
;         __builtin_amdgcn_global_load_lds((const unsigned*)((const char*)(gbase) + (voff)[_i]), (PG8_LAS unsigned*)(lds + (bufoff) + ldsw + _i * 8192), 16, 0, 0); } while (0)
; #define PG8_LDA(dst, b, h) do { _Pragma("unroll") for (int m = 0; m < 4; ++m) _Pragma("unroll") for (int k = 0; k < 2; ++k) dst[m][k] = *(const PG8_LAS bf16x8*)(lds + PG8_SA(b, h) + aoff + m * 2048 + k * 1024); } while (0)
; #define PG8_LDB(dst, b, h) do { _Pragma("unroll") for (int n = 0; n < 2; ++n) _Pragma("unroll") for (int k = 0; k < 2; ++k) dst[n][k] = *(const PG8_LAS bf16x8*)(lds + PG8_SB(b, h) + boff + n * 2048 + k * 1024); } while (0)
; #define PG8_MMA(ai, bj, At, Bt) do { __builtin_amdgcn_s_setprio(1); _Pragma("unroll") for (int m = 0; m < 4; ++m) _Pragma("unroll") for (int n = 0; n < 2; ++n) _Pragma("unroll") for (int k = 0; k < 2; ++k) \
;         acc[ai][bj][m][n] = __builtin_amdgcn_mfma_f32_16x16x32_bf16(Bt[n][k], At[m][k], acc[ai][bj][m][n], 0, 0, 0); __builtin_amdgcn_s_setprio(0); } while (0)
; #define PG8_WAIT_V(n) asm volatile("s_waitcnt vmcnt(" #n ")" ::: "memory")
; #define PG8_BAR __builtin_amdgcn_s_barrier()
; template <class Epi, class Sched, bool ALIGN_EPI = false, bool SP2 = false>
; __device__ __forceinline__ void gemm_phase(PG8_LAS unsigned char* lds, const Gemm g, const Sched& S, const Epi& E) {
;     ...
;         for (int t = 0; t < nt; t += 2) {
;             const bool last = (t == nt - 2);
;             const char* a1 = cA + (size_t)(t + 1) * kstep;
;             const char* a2 = last ? nA : cA + (size_t)(t + 2) * kstep; const char* b2 = last ? nB : cB + (size_t)(t + 2) * kstep;
;             const char* a3 = a2 + kstep; const char* b3 = b2 + kstep;
;             if (last && has_next) S.a_ready(nxt);
;             if constexpr (SP2) {
;             PG8_LDB(B0, 0, 0); PG8_LDB(B1, 0, 1); PG8_SCHED; PG8_LDA(At, 0, 0); PG8_STAGE(PG8_SA(1, 1), a1 + hstep, voffA);
;             PG8_WAIT_V(8); PG8_WAIT_L(0); PG8_BAR; PG8_MMA(0, 0, At, B0); PG8_MMA(0, 1, At, B1); PG8_BAR; PG8_SCHED;
;             PG8_LDA(At, 0, 1); PG8_STAGE(PG8_SB(0, 0), b2, voffB); PG8_STAGE(PG8_SB(0, 1), b2 + hstep, voffB); PG8_STAGE(PG8_SA(0, 0), a2, voffA);
;             PG8_WAIT_V(8); PG8_WAIT_L(0); PG8_BAR; PG8_MMA(1, 0, At, B0); PG8_MMA(1, 1, At, B1); PG8_BAR; PG8_SCHED;
.LBB0_242:
	s_add_u32 s79, s86, 0xfffc0080
	s_addc_u32 s85, s87, -1
	s_add_i32 s92, 0, 0x10000
	s_cmp_eq_u32 s77, 12
	s_cselect_b32 s91, s49, s85
	s_cselect_b32 s90, s54, s79
	v_add_u32_e32 v144, s92, v146
	s_cselect_b32 s89, s55, s65
	s_cselect_b32 s88, s61, s64
	s_add_i32 s79, 0, 0x14000
	ds_read_b128 v[140:143], v144
	ds_read_b128 v[150:153], v144 offset:1024
	ds_read_b128 v[154:157], v144 offset:2048
	ds_read_b128 v[158:161], v144 offset:3072
	v_add_u32_e32 v144, s79, v146
	ds_read_b128 v[162:165], v144
	ds_read_b128 v[166:169], v144 offset:1024
	ds_read_b128 v[170:173], v144 offset:2048
	ds_read_b128 v[174:177], v144 offset:3072
	v_lshl_add_u64 v[212:213], s[86:87], 0, v[136:137]
	s_add_i32 m0, s7, 0xc000
	ds_read_b128 v[178:181], v149
	ds_read_b128 v[182:185], v149 offset:1024
	ds_read_b128 v[186:189], v149 offset:2048
	ds_read_b128 v[190:193], v149 offset:3072
	ds_read_b128 v[194:197], v149 offset:4096
	ds_read_b128 v[198:201], v149 offset:5120
	ds_read_b128 v[202:205], v149 offset:6144
	ds_read_b128 v[208:211], v149 offset:7168
	global_load_lds_dwordx4 v[212:213], off
	s_add_i32 m0, s7, 0xe000
	v_lshl_add_u64 v[212:213], s[86:87], 0, v[138:139]
	global_load_lds_dwordx4 v[212:213], off
	s_waitcnt vmcnt(8)
	s_waitcnt lgkmcnt(0)
	s_barrier
	s_setprio 1
	s_waitcnt lgkmcnt(0)
	v_mfma_f32_16x16x32_bf16 v[126:129], v[140:143], v[178:181], v[126:129]
	v_mfma_f32_16x16x32_bf16 v[122:125], v[154:157], v[178:181], v[122:125]
	v_mfma_f32_16x16x32_bf16 v[110:113], v[140:143], v[186:189], v[110:113]
	v_mfma_f32_16x16x32_bf16 v[106:109], v[154:157], v[186:189], v[106:109]
	v_mfma_f32_16x16x32_bf16 v[94:97], v[140:143], v[194:197], v[94:97]
	v_mfma_f32_16x16x32_bf16 v[90:93], v[154:157], v[194:197], v[90:93]
	v_mfma_f32_16x16x32_bf16 v[78:81], v[140:143], v[202:205], v[78:81]
	v_mfma_f32_16x16x32_bf16 v[74:77], v[154:157], v[202:205], v[74:77]
	v_mfma_f32_16x16x32_bf16 v[126:129], v[150:153], v[182:185], v[126:129]
	v_mfma_f32_16x16x32_bf16 v[122:125], v[158:161], v[182:185], v[122:125]
	v_mfma_f32_16x16x32_bf16 v[110:113], v[150:153], v[190:193], v[110:113]
	v_mfma_f32_16x16x32_bf16 v[106:109], v[158:161], v[190:193], v[106:109]
	v_mfma_f32_16x16x32_bf16 v[94:97], v[150:153], v[198:201], v[94:97]
	v_mfma_f32_16x16x32_bf16 v[90:93], v[158:161], v[198:201], v[90:93]
	v_mfma_f32_16x16x32_bf16 v[78:81], v[150:153], v[208:211], v[78:81]
	v_mfma_f32_16x16x32_bf16 v[74:77], v[158:161], v[208:211], v[74:77]
	s_setprio 0
	s_setprio 1
	v_mfma_f32_16x16x32_bf16 v[118:121], v[162:165], v[178:181], v[118:121]
	v_mfma_f32_16x16x32_bf16 v[114:117], v[170:173], v[178:181], v[114:117]
	v_mfma_f32_16x16x32_bf16 v[102:105], v[162:165], v[186:189], v[102:105]
	v_mfma_f32_16x16x32_bf16 v[98:101], v[170:173], v[186:189], v[98:101]
	v_mfma_f32_16x16x32_bf16 v[86:89], v[162:165], v[194:197], v[86:89]
	v_mfma_f32_16x16x32_bf16 v[82:85], v[170:173], v[194:197], v[82:85]
	v_mfma_f32_16x16x32_bf16 v[70:73], v[162:165], v[202:205], v[70:73]
	v_mfma_f32_16x16x32_bf16 v[66:69], v[170:173], v[202:205], v[66:69]
	v_mfma_f32_16x16x32_bf16 v[118:121], v[166:169], v[182:185], v[118:121]
	v_mfma_f32_16x16x32_bf16 v[114:117], v[174:177], v[182:185], v[114:117]
	v_mfma_f32_16x16x32_bf16 v[102:105], v[166:169], v[190:193], v[102:105]
	v_mfma_f32_16x16x32_bf16 v[98:101], v[174:177], v[190:193], v[98:101]
	v_mfma_f32_16x16x32_bf16 v[86:89], v[166:169], v[198:201], v[86:89]
	v_mfma_f32_16x16x32_bf16 v[82:85], v[174:177], v[198:201], v[82:85]
	v_mfma_f32_16x16x32_bf16 v[70:73], v[166:169], v[208:211], v[70:73]
	v_mfma_f32_16x16x32_bf16 v[66:69], v[174:177], v[208:211], v[66:69]
	s_setprio 0
	s_barrier
	s_add_i32 s85, s92, s14
	v_lshl_add_u64 v[212:213], s[88:89], 0, v[0:1]
	s_mov_b32 m0, s85
	ds_read_b128 v[178:181], v149 offset:16384
	ds_read_b128 v[182:185], v149 offset:17408
	ds_read_b128 v[186:189], v149 offset:18432
	ds_read_b128 v[190:193], v149 offset:19456
	ds_read_b128 v[194:197], v149 offset:20480
	ds_read_b128 v[198:201], v149 offset:21504
	ds_read_b128 v[202:205], v149 offset:22528
	ds_read_b128 v[208:211], v149 offset:23552
	global_load_lds_dwordx4 v[212:213], off
	s_add_i32 m0, s85, 0x2000
	s_add_u32 s92, s88, 0x40000
	v_lshl_add_u64 v[214:215], s[88:89], 0, v[134:135]
	s_addc_u32 s93, s89, 0
	s_add_i32 s79, s79, s14
	global_load_lds_dwordx4 v[214:215], off
	v_lshl_add_u64 v[216:217], s[92:93], 0, v[0:1]
	s_mov_b32 m0, s79
	v_lshl_add_u64 v[218:219], s[90:91], 0, v[132:133]
	global_load_lds_dwordx4 v[216:217], off
	s_add_i32 m0, s79, 0x2000
	v_lshl_add_u64 v[216:217], s[92:93], 0, v[134:135]
	global_load_lds_dwordx4 v[216:217], off
	s_mov_b32 m0, s7
	v_lshl_add_u64 v[216:217], s[90:91], 0, v[130:131]
	global_load_lds_dwordx4 v[216:217], off
	s_mov_b32 m0, s28
	s_nop 0
	global_load_lds_dwordx4 v[218:219], off
	s_waitcnt vmcnt(8)
	s_waitcnt lgkmcnt(0)
	s_barrier
; #define PG8_STAGE(bufoff, gbase, voff) do { _Pragma("unroll") for (int _i = 0; _i < 2; ++_i) \
;         __builtin_amdgcn_global_load_lds((const unsigned*)((const char*)(gbase) + (voff)[_i]), (PG8_LAS unsigned*)(lds + (bufoff) + ldsw + _i * 8192), 16, 0, 0); } while (0)
; #define PG8_LDA(dst, b, h) do { _Pragma("unroll") for (int m = 0; m < 4; ++m) _Pragma("unroll") for (int k = 0; k < 2; ++k) dst[m][k] = *(const PG8_LAS bf16x8*)(lds + PG8_SA(b, h) + aoff + m * 2048 + k * 1024); } while (0)
; #define PG8_LDB(dst, b, h) do { _Pragma("unroll") for (int n = 0; n < 2; ++n) _Pragma("unroll") for (int k = 0; k < 2; ++k) dst[n][k] = *(const PG8_LAS bf16x8*)(lds + PG8_SB(b, h) + boff + n * 2048 + k * 1024); } while (0)
; #define PG8_MMA(ai, bj, At, Bt) do { __builtin_amdgcn_s_setprio(1); _Pragma("unroll") for (int m = 0; m < 4; ++m) _Pragma("unroll") for (int n = 0; n < 2; ++n) _Pragma("unroll") for (int k = 0; k < 2; ++k) \
;         acc[ai][bj][m][n] = __builtin_amdgcn_mfma_f32_16x16x32_bf16(Bt[n][k], At[m][k], acc[ai][bj][m][n], 0, 0, 0); __builtin_amdgcn_s_setprio(0); } while (0)
; #define PG8_WAIT_V(n) asm volatile("s_waitcnt vmcnt(" #n ")" ::: "memory")
; #define PG8_WAIT_L(n) asm volatile("s_waitcnt lgkmcnt(" #n ")" ::: "memory")
; #define PG8_BAR __builtin_amdgcn_s_barrier()
; #define PG8_SCHED __builtin_amdgcn_sched_barrier(0)
; template <class Epi, class Sched, bool ALIGN_EPI = false, bool SP2 = false>
; __device__ __forceinline__ void gemm_phase(PG8_LAS unsigned char* lds, const Gemm g, const Sched& S, const Epi& E) {
;     ...
;             PG8_WAIT_V(8); PG8_WAIT_L(0); PG8_BAR; PG8_MMA(1, 0, At, B0); PG8_MMA(1, 1, At, B1); PG8_BAR; PG8_SCHED;
;             PG8_LDB(B0, 1, 0); PG8_LDB(B1, 1, 1); PG8_SCHED; PG8_LDA(At, 1, 0); PG8_STAGE(PG8_SA(0, 1), a2 + hstep, voffA);
;             PG8_WAIT_V(8); PG8_WAIT_L(0); PG8_BAR; PG8_MMA(0, 0, At, B0); PG8_MMA(0, 1, At, B1); PG8_BAR; PG8_SCHED;
	s_setprio 1
	s_waitcnt lgkmcnt(0)
	v_mfma_f32_16x16x32_bf16 v[62:65], v[140:143], v[178:181], v[62:65]
	v_mfma_f32_16x16x32_bf16 v[58:61], v[154:157], v[178:181], v[58:61]
	v_mfma_f32_16x16x32_bf16 v[46:49], v[140:143], v[186:189], v[46:49]
	v_mfma_f32_16x16x32_bf16 v[42:45], v[154:157], v[186:189], v[42:45]
	v_mfma_f32_16x16x32_bf16 v[30:33], v[140:143], v[194:197], v[30:33]
	v_mfma_f32_16x16x32_bf16 v[26:29], v[154:157], v[194:197], v[26:29]
	v_mfma_f32_16x16x32_bf16 v[14:17], v[140:143], v[202:205], v[14:17]
	v_mfma_f32_16x16x32_bf16 v[10:13], v[154:157], v[202:205], v[10:13]
	v_mfma_f32_16x16x32_bf16 v[62:65], v[150:153], v[182:185], v[62:65]
	v_mfma_f32_16x16x32_bf16 v[58:61], v[158:161], v[182:185], v[58:61]
	v_mfma_f32_16x16x32_bf16 v[46:49], v[150:153], v[190:193], v[46:49]
	v_mfma_f32_16x16x32_bf16 v[42:45], v[158:161], v[190:193], v[42:45]
	v_mfma_f32_16x16x32_bf16 v[30:33], v[150:153], v[198:201], v[30:33]
	v_mfma_f32_16x16x32_bf16 v[26:29], v[158:161], v[198:201], v[26:29]
	v_mfma_f32_16x16x32_bf16 v[14:17], v[150:153], v[208:211], v[14:17]
	v_mfma_f32_16x16x32_bf16 v[10:13], v[158:161], v[208:211], v[10:13]
	s_setprio 0
	s_setprio 1
	v_mfma_f32_16x16x32_bf16 v[54:57], v[162:165], v[178:181], v[54:57]
	v_mfma_f32_16x16x32_bf16 v[50:53], v[170:173], v[178:181], v[50:53]
	v_mfma_f32_16x16x32_bf16 v[38:41], v[162:165], v[186:189], v[38:41]
	v_mfma_f32_16x16x32_bf16 v[34:37], v[170:173], v[186:189], v[34:37]
	v_mfma_f32_16x16x32_bf16 v[22:25], v[162:165], v[194:197], v[22:25]
	v_mfma_f32_16x16x32_bf16 v[18:21], v[170:173], v[194:197], v[18:21]
	v_mfma_f32_16x16x32_bf16 v[6:9], v[162:165], v[202:205], v[6:9]
	v_mfma_f32_16x16x32_bf16 v[2:5], v[170:173], v[202:205], v[2:5]
	v_mfma_f32_16x16x32_bf16 v[54:57], v[166:169], v[182:185], v[54:57]
	v_mfma_f32_16x16x32_bf16 v[50:53], v[174:177], v[182:185], v[50:53]
	v_mfma_f32_16x16x32_bf16 v[38:41], v[166:169], v[190:193], v[38:41]
	v_mfma_f32_16x16x32_bf16 v[34:37], v[174:177], v[190:193], v[34:37]
	v_mfma_f32_16x16x32_bf16 v[22:25], v[166:169], v[198:201], v[22:25]
	v_mfma_f32_16x16x32_bf16 v[18:21], v[174:177], v[198:201], v[18:21]
	v_mfma_f32_16x16x32_bf16 v[6:9], v[166:169], v[208:211], v[6:9]
	v_mfma_f32_16x16x32_bf16 v[2:5], v[174:177], v[208:211], v[2:5]
	s_setprio 0
	s_barrier
	s_add_i32 s79, 0, 0x18000
	v_add_u32_e32 v144, s79, v146
	s_add_i32 s85, 0, 0x1c000
	ds_read_b128 v[140:143], v144
	ds_read_b128 v[150:153], v144 offset:1024
	ds_read_b128 v[154:157], v144 offset:2048
	ds_read_b128 v[158:161], v144 offset:3072
	v_add_u32_e32 v144, s85, v146
	ds_read_b128 v[162:165], v144
	ds_read_b128 v[166:169], v144 offset:1024
	ds_read_b128 v[170:173], v144 offset:2048
	ds_read_b128 v[174:177], v144 offset:3072
	s_add_u32 s90, s90, 0x40000
	s_addc_u32 s91, s91, 0
	s_mov_b32 m0, s29
	v_lshl_add_u64 v[220:221], s[90:91], 0, v[130:131]
	ds_read_b128 v[178:181], v149 offset:32768
	ds_read_b128 v[182:185], v149 offset:33792
	ds_read_b128 v[186:189], v149 offset:34816
	ds_read_b128 v[190:193], v149 offset:35840
	ds_read_b128 v[194:197], v149 offset:36864
	ds_read_b128 v[198:201], v149 offset:37888
	ds_read_b128 v[202:205], v149 offset:38912
	ds_read_b128 v[208:211], v149 offset:39936
	global_load_lds_dwordx4 v[220:221], off
	s_mov_b32 m0, s42
	v_lshl_add_u64 v[220:221], s[90:91], 0, v[132:133]
	global_load_lds_dwordx4 v[220:221], off
	s_waitcnt vmcnt(8)
	s_waitcnt lgkmcnt(0)
	s_barrier
	s_setprio 1
	s_waitcnt lgkmcnt(0)
	v_mfma_f32_16x16x32_bf16 v[126:129], v[140:143], v[178:181], v[126:129]
	v_mfma_f32_16x16x32_bf16 v[122:125], v[154:157], v[178:181], v[122:125]
	v_mfma_f32_16x16x32_bf16 v[110:113], v[140:143], v[186:189], v[110:113]
	v_mfma_f32_16x16x32_bf16 v[106:109], v[154:157], v[186:189], v[106:109]
	v_mfma_f32_16x16x32_bf16 v[94:97], v[140:143], v[194:197], v[94:97]
	v_mfma_f32_16x16x32_bf16 v[90:93], v[154:157], v[194:197], v[90:93]
	v_mfma_f32_16x16x32_bf16 v[78:81], v[140:143], v[202:205], v[78:81]
	v_mfma_f32_16x16x32_bf16 v[74:77], v[154:157], v[202:205], v[74:77]
	v_mfma_f32_16x16x32_bf16 v[126:129], v[150:153], v[182:185], v[126:129]
	v_mfma_f32_16x16x32_bf16 v[122:125], v[158:161], v[182:185], v[122:125]
	v_mfma_f32_16x16x32_bf16 v[110:113], v[150:153], v[190:193], v[110:113]
	v_mfma_f32_16x16x32_bf16 v[106:109], v[158:161], v[190:193], v[106:109]
	v_mfma_f32_16x16x32_bf16 v[94:97], v[150:153], v[198:201], v[94:97]
	v_mfma_f32_16x16x32_bf16 v[90:93], v[158:161], v[198:201], v[90:93]
	v_mfma_f32_16x16x32_bf16 v[78:81], v[150:153], v[208:211], v[78:81]
	v_mfma_f32_16x16x32_bf16 v[74:77], v[158:161], v[208:211], v[74:77]
	s_setprio 0
	s_setprio 1
	v_mfma_f32_16x16x32_bf16 v[118:121], v[162:165], v[178:181], v[118:121]
	v_mfma_f32_16x16x32_bf16 v[114:117], v[170:173], v[178:181], v[114:117]
	v_mfma_f32_16x16x32_bf16 v[102:105], v[162:165], v[186:189], v[102:105]
	v_mfma_f32_16x16x32_bf16 v[98:101], v[170:173], v[186:189], v[98:101]
	v_mfma_f32_16x16x32_bf16 v[86:89], v[162:165], v[194:197], v[86:89]
	v_mfma_f32_16x16x32_bf16 v[82:85], v[170:173], v[194:197], v[82:85]
	v_mfma_f32_16x16x32_bf16 v[70:73], v[162:165], v[202:205], v[70:73]
	v_mfma_f32_16x16x32_bf16 v[66:69], v[170:173], v[202:205], v[66:69]
	v_mfma_f32_16x16x32_bf16 v[118:121], v[166:169], v[182:185], v[118:121]
	v_mfma_f32_16x16x32_bf16 v[114:117], v[174:177], v[182:185], v[114:117]
	v_mfma_f32_16x16x32_bf16 v[102:105], v[166:169], v[190:193], v[102:105]
	v_mfma_f32_16x16x32_bf16 v[98:101], v[174:177], v[190:193], v[98:101]
	v_mfma_f32_16x16x32_bf16 v[86:89], v[166:169], v[198:201], v[86:89]
	v_mfma_f32_16x16x32_bf16 v[82:85], v[174:177], v[198:201], v[82:85]
	v_mfma_f32_16x16x32_bf16 v[70:73], v[166:169], v[208:211], v[70:73]
	v_mfma_f32_16x16x32_bf16 v[66:69], v[174:177], v[208:211], v[66:69]
	s_setprio 0
	s_barrier
; #define PG8_STAGE(bufoff, gbase, voff) do { _Pragma("unroll") for (int _i = 0; _i < 2; ++_i) \
;         __builtin_amdgcn_global_load_lds((const unsigned*)((const char*)(gbase) + (voff)[_i]), (PG8_LAS unsigned*)(lds + (bufoff) + ldsw + _i * 8192), 16, 0, 0); } while (0)
; #define PG8_LDA(dst, b, h) do { _Pragma("unroll") for (int m = 0; m < 4; ++m) _Pragma("unroll") for (int k = 0; k < 2; ++k) dst[m][k] = *(const PG8_LAS bf16x8*)(lds + PG8_SA(b, h) + aoff + m * 2048 + k * 1024); } while (0)
; #define PG8_MMA(ai, bj, At, Bt) do { __builtin_amdgcn_s_setprio(1); _Pragma("unroll") for (int m = 0; m < 4; ++m) _Pragma("unroll") for (int n = 0; n < 2; ++n) _Pragma("unroll") for (int k = 0; k < 2; ++k) \
;         acc[ai][bj][m][n] = __builtin_amdgcn_mfma_f32_16x16x32_bf16(Bt[n][k], At[m][k], acc[ai][bj][m][n], 0, 0, 0); __builtin_amdgcn_s_setprio(0); } while (0)
; #define PG8_WAIT_V(n) asm volatile("s_waitcnt vmcnt(" #n ")" ::: "memory")
; #define PG8_WAIT_L(n) asm volatile("s_waitcnt lgkmcnt(" #n ")" ::: "memory")
; #define PG8_BAR __builtin_amdgcn_s_barrier()
; #define PG8_SCHED __builtin_amdgcn_sched_barrier(0)
; template <class Epi, class Sched, bool ALIGN_EPI = false, bool SP2 = false>
; __device__ __forceinline__ void gemm_phase(PG8_LAS unsigned char* lds, const Gemm g, const Sched& S, const Epi& E) {
;     ...
;             PG8_LDA(At, 1, 1); PG8_STAGE(PG8_SB(1, 0), b3, voffB); PG8_STAGE(PG8_SB(1, 1), b3 + hstep, voffB); PG8_STAGE(PG8_SA(1, 0), a3, voffA);
;             PG8_WAIT_V(8); PG8_WAIT_L(0); PG8_BAR; PG8_MMA(1, 0, At, B0); PG8_MMA(1, 1, At, B1); PG8_BAR; PG8_SCHED;
	s_add_i32 s79, s79, s14
	v_lshl_add_u64 v[212:213], v[212:213], 0, s[24:25]
	s_mov_b32 m0, s79
	ds_read_b128 v[178:181], v149 offset:49152
	ds_read_b128 v[182:185], v149 offset:50176
	ds_read_b128 v[186:189], v149 offset:51200
	ds_read_b128 v[190:193], v149 offset:52224
	ds_read_b128 v[194:197], v149 offset:53248
	ds_read_b128 v[198:201], v149 offset:54272
	ds_read_b128 v[202:205], v149 offset:55296
	ds_read_b128 v[208:211], v149 offset:56320
	global_load_lds_dwordx4 v[212:213], off
	s_add_i32 m0, s79, 0x2000
	s_add_u32 s88, s88, 0x40080
	v_lshl_add_u64 v[212:213], v[214:215], 0, s[24:25]
	s_addc_u32 s89, s89, 0
	s_add_i32 s79, s85, s14
	global_load_lds_dwordx4 v[212:213], off
	s_mov_b32 m0, s79
	v_lshl_add_u64 v[212:213], s[88:89], 0, v[0:1]
	global_load_lds_dwordx4 v[212:213], off
	s_add_i32 m0, s79, 0x2000
	v_lshl_add_u64 v[212:213], s[88:89], 0, v[134:135]
	global_load_lds_dwordx4 v[212:213], off
	s_mov_b32 m0, s43
	v_lshl_add_u64 v[212:213], v[216:217], 0, s[24:25]
	global_load_lds_dwordx4 v[212:213], off
	s_mov_b32 m0, s44
	v_lshl_add_u64 v[212:213], v[218:219], 0, s[24:25]
	global_load_lds_dwordx4 v[212:213], off
	s_waitcnt vmcnt(8)
	s_waitcnt lgkmcnt(0)
	s_barrier
	s_setprio 1
	s_waitcnt lgkmcnt(0)
	v_mfma_f32_16x16x32_bf16 v[62:65], v[140:143], v[178:181], v[62:65]
	v_mfma_f32_16x16x32_bf16 v[58:61], v[154:157], v[178:181], v[58:61]
	v_mfma_f32_16x16x32_bf16 v[46:49], v[140:143], v[186:189], v[46:49]
	v_mfma_f32_16x16x32_bf16 v[42:45], v[154:157], v[186:189], v[42:45]
	v_mfma_f32_16x16x32_bf16 v[30:33], v[140:143], v[194:197], v[30:33]
	v_mfma_f32_16x16x32_bf16 v[26:29], v[154:157], v[194:197], v[26:29]
	v_mfma_f32_16x16x32_bf16 v[14:17], v[140:143], v[202:205], v[14:17]
	v_mfma_f32_16x16x32_bf16 v[10:13], v[154:157], v[202:205], v[10:13]
	v_mfma_f32_16x16x32_bf16 v[62:65], v[150:153], v[182:185], v[62:65]
	v_mfma_f32_16x16x32_bf16 v[58:61], v[158:161], v[182:185], v[58:61]
	v_mfma_f32_16x16x32_bf16 v[46:49], v[150:153], v[190:193], v[46:49]
	v_mfma_f32_16x16x32_bf16 v[42:45], v[158:161], v[190:193], v[42:45]
	v_mfma_f32_16x16x32_bf16 v[30:33], v[150:153], v[198:201], v[30:33]
	v_mfma_f32_16x16x32_bf16 v[26:29], v[158:161], v[198:201], v[26:29]
	v_mfma_f32_16x16x32_bf16 v[14:17], v[150:153], v[208:211], v[14:17]
	v_mfma_f32_16x16x32_bf16 v[10:13], v[158:161], v[208:211], v[10:13]
	s_setprio 0
	s_setprio 1
	v_mfma_f32_16x16x32_bf16 v[54:57], v[162:165], v[178:181], v[54:57]
	v_mfma_f32_16x16x32_bf16 v[50:53], v[170:173], v[178:181], v[50:53]
	v_mfma_f32_16x16x32_bf16 v[38:41], v[162:165], v[186:189], v[38:41]
	v_mfma_f32_16x16x32_bf16 v[34:37], v[170:173], v[186:189], v[34:37]
	v_mfma_f32_16x16x32_bf16 v[22:25], v[162:165], v[194:197], v[22:25]
	v_mfma_f32_16x16x32_bf16 v[18:21], v[170:173], v[194:197], v[18:21]
	v_mfma_f32_16x16x32_bf16 v[6:9], v[162:165], v[202:205], v[6:9]
	v_mfma_f32_16x16x32_bf16 v[2:5], v[170:173], v[202:205], v[2:5]
	v_mfma_f32_16x16x32_bf16 v[54:57], v[166:169], v[182:185], v[54:57]
	v_mfma_f32_16x16x32_bf16 v[50:53], v[174:177], v[182:185], v[50:53]
	v_mfma_f32_16x16x32_bf16 v[38:41], v[166:169], v[190:193], v[38:41]
	v_mfma_f32_16x16x32_bf16 v[34:37], v[174:177], v[190:193], v[34:37]
	v_mfma_f32_16x16x32_bf16 v[22:25], v[166:169], v[198:201], v[22:25]
	v_mfma_f32_16x16x32_bf16 v[18:21], v[174:177], v[198:201], v[18:21]
	v_mfma_f32_16x16x32_bf16 v[6:9], v[166:169], v[208:211], v[6:9]
	v_mfma_f32_16x16x32_bf16 v[2:5], v[174:177], v[208:211], v[2:5]
	s_setprio 0
	s_barrier
	s_add_i32 s77, s77, 2
	s_add_u32 s86, s86, 0x100
	s_addc_u32 s87, s87, 0
	s_add_u32 s64, s64, 0x100
	s_addc_u32 s65, s65, 0
	s_cmp_gt_u32 s77, 13
	s_cbranch_scc0 .LBB0_242
	s_and_b64 vcc, exec, s[74:75]
	s_cbranch_vccz .LBB0_245
	s_barrier

; #define PG8_STAGE(bufoff, gbase, voff) do { _Pragma("unroll") for (int _i = 0; _i < 2; ++_i) \
;         __builtin_amdgcn_global_load_lds((const unsigned*)((const char*)(gbase) + (voff)[_i]), (PG8_LAS unsigned*)(lds + (bufoff) + ldsw + _i * 8192), 16, 0, 0); } while (0)
; #define PG8_LDA(dst, b, h) do { _Pragma("unroll") for (int m = 0; m < 4; ++m) _Pragma("unroll") for (int k = 0; k < 2; ++k) dst[m][k] = *(const PG8_LAS bf16x8*)(lds + PG8_SA(b, h) + aoff + m * 2048 + k * 1024); } while (0)
; #define PG8_LDB(dst, b, h) do { _Pragma("unroll") for (int n = 0; n < 2; ++n) _Pragma("unroll") for (int k = 0; k < 2; ++k) dst[n][k] = *(const PG8_LAS bf16x8*)(lds + PG8_SB(b, h) + boff + n * 2048 + k * 1024); } while (0)
; #define PG8_MMA(ai, bj, At, Bt) do { __builtin_amdgcn_s_setprio(1); _Pragma("unroll") for (int m = 0; m < 4; ++m) _Pragma("unroll") for (int n = 0; n < 2; ++n) _Pragma("unroll") for (int k = 0; k < 2; ++k) \
;         acc[ai][bj][m][n] = __builtin_amdgcn_mfma_f32_16x16x32_bf16(Bt[n][k], At[m][k], acc[ai][bj][m][n], 0, 0, 0); __builtin_amdgcn_s_setprio(0); } while (0)
; #define PG8_WAIT_V(n) asm volatile("s_waitcnt vmcnt(" #n ")" ::: "memory")
; #define PG8_BAR __builtin_amdgcn_s_barrier()
; template <class Epi, class Sched, bool ALIGN_EPI = false, bool SP2 = false>
; __device__ __forceinline__ void gemm_phase(PG8_LAS unsigned char* lds, const Gemm g, const Sched& S, const Epi& E) {
;     ...
;         for (int t = 0; t < nt; t += 2) {
;             const bool last = (t == nt - 2);
;             const char* a1 = cA + (size_t)(t + 1) * kstep;
;             const char* a2 = last ? nA : cA + (size_t)(t + 2) * kstep; const char* b2 = last ? nB : cB + (size_t)(t + 2) * kstep;
;             const char* a3 = a2 + kstep; const char* b3 = b2 + kstep;
;             if (last && has_next) S.a_ready(nxt);
;             if constexpr (SP2) {
;             PG8_LDB(B0, 0, 0); PG8_LDB(B1, 0, 1); PG8_SCHED; PG8_LDA(At, 0, 0); PG8_STAGE(PG8_SA(1, 1), a1 + hstep, voffA);
;             PG8_WAIT_V(8); PG8_WAIT_L(0); PG8_BAR; PG8_MMA(0, 0, At, B0); PG8_MMA(0, 1, At, B1); PG8_BAR; PG8_SCHED;
;             PG8_LDA(At, 0, 1); PG8_STAGE(PG8_SB(0, 0), b2, voffB); PG8_STAGE(PG8_SB(0, 1), b2 + hstep, voffB); PG8_STAGE(PG8_SA(0, 0), a2, voffA);
;             PG8_WAIT_V(8); PG8_WAIT_L(0); PG8_BAR; PG8_MMA(1, 0, At, B0); PG8_MMA(1, 1, At, B1); PG8_BAR; PG8_SCHED;
.LBB0_320:
	s_add_i32 s67, s66, 2
	s_add_u32 s77, s86, 0x80
	s_addc_u32 s88, s87, 0
	s_add_i32 s92, 0, 0x10000
	s_cmp_eq_u32 s45, s66
	s_cselect_b32 s89, s9, s88
	s_cselect_b32 s88, s8, s77
	s_cselect_b32 s91, s85, s65
	s_cselect_b32 s90, s84, s64
	s_add_i32 s66, 0, 0x14000
	v_add_u32_e32 v130, s92, v252
	v_add_u32_e32 v158, s66, v252
	ds_read_b128 v[114:117], v130
	ds_read_b128 v[122:125], v130 offset:1024
	ds_read_b128 v[126:129], v130 offset:2048
	ds_read_b128 v[130:133], v130 offset:3072
	ds_read_b128 v[138:141], v158
	ds_read_b128 v[142:145], v158 offset:1024
	ds_read_b128 v[146:149], v158 offset:2048
	ds_read_b128 v[158:161], v158 offset:3072
	v_lshl_add_u64 v[204:205], s[86:87], 0, v[200:201]
	s_add_i32 m0, s20, 0xc000
	ds_read_b128 v[162:165], v254
	ds_read_b128 v[166:169], v254 offset:1024
	ds_read_b128 v[170:173], v254 offset:2048
	ds_read_b128 v[174:177], v254 offset:3072
	ds_read_b128 v[178:181], v254 offset:4096
	ds_read_b128 v[182:185], v254 offset:5120
	ds_read_b128 v[186:189], v254 offset:6144
	ds_read_b128 v[190:193], v254 offset:7168
	global_load_lds_dwordx4 v[204:205], off
	s_add_i32 m0, s20, 0xe000
	v_lshl_add_u64 v[204:205], s[86:87], 0, v[202:203]
	global_load_lds_dwordx4 v[204:205], off
	s_waitcnt vmcnt(8)
	s_waitcnt lgkmcnt(0)
	s_barrier
	s_setprio 1
	s_waitcnt lgkmcnt(0)
	v_mfma_f32_16x16x32_bf16 v[154:157], v[114:117], v[162:165], v[154:157]
	v_mfma_f32_16x16x32_bf16 v[150:153], v[126:129], v[162:165], v[150:153]
	v_mfma_f32_16x16x32_bf16 v[110:113], v[114:117], v[170:173], v[110:113]
	v_mfma_f32_16x16x32_bf16 v[106:109], v[126:129], v[170:173], v[106:109]
	v_mfma_f32_16x16x32_bf16 v[94:97], v[114:117], v[178:181], v[94:97]
	v_mfma_f32_16x16x32_bf16 v[90:93], v[126:129], v[178:181], v[90:93]
	v_mfma_f32_16x16x32_bf16 v[78:81], v[114:117], v[186:189], v[78:81]
	v_mfma_f32_16x16x32_bf16 v[74:77], v[126:129], v[186:189], v[74:77]
	v_mfma_f32_16x16x32_bf16 v[154:157], v[122:125], v[166:169], v[154:157]
	v_mfma_f32_16x16x32_bf16 v[150:153], v[130:133], v[166:169], v[150:153]
	v_mfma_f32_16x16x32_bf16 v[110:113], v[122:125], v[174:177], v[110:113]
	v_mfma_f32_16x16x32_bf16 v[106:109], v[130:133], v[174:177], v[106:109]
	v_mfma_f32_16x16x32_bf16 v[94:97], v[122:125], v[182:185], v[94:97]
	v_mfma_f32_16x16x32_bf16 v[90:93], v[130:133], v[182:185], v[90:93]
	v_mfma_f32_16x16x32_bf16 v[78:81], v[122:125], v[190:193], v[78:81]
	v_mfma_f32_16x16x32_bf16 v[74:77], v[130:133], v[190:193], v[74:77]
	s_setprio 0
	s_setprio 1
	v_mfma_f32_16x16x32_bf16 v[134:137], v[138:141], v[162:165], v[134:137]
	v_mfma_f32_16x16x32_bf16 v[118:121], v[146:149], v[162:165], v[118:121]
	v_mfma_f32_16x16x32_bf16 v[102:105], v[138:141], v[170:173], v[102:105]
	v_mfma_f32_16x16x32_bf16 v[98:101], v[146:149], v[170:173], v[98:101]
	v_mfma_f32_16x16x32_bf16 v[86:89], v[138:141], v[178:181], v[86:89]
	v_mfma_f32_16x16x32_bf16 v[82:85], v[146:149], v[178:181], v[82:85]
	v_mfma_f32_16x16x32_bf16 v[70:73], v[138:141], v[186:189], v[70:73]
	v_mfma_f32_16x16x32_bf16 v[66:69], v[146:149], v[186:189], v[66:69]
	v_mfma_f32_16x16x32_bf16 v[134:137], v[142:145], v[166:169], v[134:137]
	v_mfma_f32_16x16x32_bf16 v[118:121], v[158:161], v[166:169], v[118:121]
	v_mfma_f32_16x16x32_bf16 v[102:105], v[142:145], v[174:177], v[102:105]
	v_mfma_f32_16x16x32_bf16 v[98:101], v[158:161], v[174:177], v[98:101]
	v_mfma_f32_16x16x32_bf16 v[86:89], v[142:145], v[182:185], v[86:89]
	v_mfma_f32_16x16x32_bf16 v[82:85], v[158:161], v[182:185], v[82:85]
	v_mfma_f32_16x16x32_bf16 v[70:73], v[142:145], v[190:193], v[70:73]
	v_mfma_f32_16x16x32_bf16 v[66:69], v[158:161], v[190:193], v[66:69]
	s_setprio 0
	s_barrier
	s_add_i32 s77, s92, s15
	v_lshl_add_u64 v[204:205], s[90:91], 0, v[0:1]
	s_mov_b32 m0, s77
	ds_read_b128 v[162:165], v254 offset:16384
	ds_read_b128 v[166:169], v254 offset:17408
	ds_read_b128 v[170:173], v254 offset:18432
	ds_read_b128 v[174:177], v254 offset:19456
	ds_read_b128 v[178:181], v254 offset:20480
	ds_read_b128 v[182:185], v254 offset:21504
	ds_read_b128 v[186:189], v254 offset:22528
	ds_read_b128 v[190:193], v254 offset:23552
	global_load_lds_dwordx4 v[204:205], off
	s_add_i32 m0, s77, 0x2000
	v_lshl_add_u64 v[208:209], s[90:91], 0, v[198:199]
	s_add_u32 s90, s90, s76
	s_addc_u32 s91, s91, 0
	s_add_i32 s66, s66, s15
	global_load_lds_dwordx4 v[208:209], off
	v_lshl_add_u64 v[210:211], s[90:91], 0, v[0:1]
	s_mov_b32 m0, s66
	v_lshl_add_u64 v[212:213], s[90:91], 0, v[198:199]
	global_load_lds_dwordx4 v[210:211], off
	s_add_i32 m0, s66, 0x2000
	v_lshl_add_u64 v[214:215], s[88:89], 0, v[194:195]
	global_load_lds_dwordx4 v[212:213], off
	s_mov_b32 m0, s20
	v_lshl_add_u64 v[216:217], s[88:89], 0, v[196:197]
	global_load_lds_dwordx4 v[214:215], off
	s_mov_b32 m0, s26
	s_nop 0
	global_load_lds_dwordx4 v[216:217], off
	s_waitcnt vmcnt(8)
	s_waitcnt lgkmcnt(0)
	s_barrier
; #define PG8_STAGE(bufoff, gbase, voff) do { _Pragma("unroll") for (int _i = 0; _i < 2; ++_i) \
;         __builtin_amdgcn_global_load_lds((const unsigned*)((const char*)(gbase) + (voff)[_i]), (PG8_LAS unsigned*)(lds + (bufoff) + ldsw + _i * 8192), 16, 0, 0); } while (0)
; #define PG8_LDA(dst, b, h) do { _Pragma("unroll") for (int m = 0; m < 4; ++m) _Pragma("unroll") for (int k = 0; k < 2; ++k) dst[m][k] = *(const PG8_LAS bf16x8*)(lds + PG8_SA(b, h) + aoff + m * 2048 + k * 1024); } while (0)
; #define PG8_LDB(dst, b, h) do { _Pragma("unroll") for (int n = 0; n < 2; ++n) _Pragma("unroll") for (int k = 0; k < 2; ++k) dst[n][k] = *(const PG8_LAS bf16x8*)(lds + PG8_SB(b, h) + boff + n * 2048 + k * 1024); } while (0)
; #define PG8_MMA(ai, bj, At, Bt) do { __builtin_amdgcn_s_setprio(1); _Pragma("unroll") for (int m = 0; m < 4; ++m) _Pragma("unroll") for (int n = 0; n < 2; ++n) _Pragma("unroll") for (int k = 0; k < 2; ++k) \
;         acc[ai][bj][m][n] = __builtin_amdgcn_mfma_f32_16x16x32_bf16(Bt[n][k], At[m][k], acc[ai][bj][m][n], 0, 0, 0); __builtin_amdgcn_s_setprio(0); } while (0)
; #define PG8_WAIT_V(n) asm volatile("s_waitcnt vmcnt(" #n ")" ::: "memory")
; #define PG8_WAIT_L(n) asm volatile("s_waitcnt lgkmcnt(" #n ")" ::: "memory")
; #define PG8_BAR __builtin_amdgcn_s_barrier()
; #define PG8_SCHED __builtin_amdgcn_sched_barrier(0)
; template <class Epi, class Sched, bool ALIGN_EPI = false, bool SP2 = false>
; __device__ __forceinline__ void gemm_phase(PG8_LAS unsigned char* lds, const Gemm g, const Sched& S, const Epi& E) {
;     ...
;             PG8_WAIT_V(8); PG8_WAIT_L(0); PG8_BAR; PG8_MMA(1, 0, At, B0); PG8_MMA(1, 1, At, B1); PG8_BAR; PG8_SCHED;
;             PG8_LDB(B0, 1, 0); PG8_LDB(B1, 1, 1); PG8_SCHED; PG8_LDA(At, 1, 0); PG8_STAGE(PG8_SA(0, 1), a2 + hstep, voffA);
;             PG8_WAIT_V(8); PG8_WAIT_L(0); PG8_BAR; PG8_MMA(0, 0, At, B0); PG8_MMA(0, 1, At, B1); PG8_BAR; PG8_SCHED;
	s_setprio 1
	s_waitcnt lgkmcnt(0)
	v_mfma_f32_16x16x32_bf16 v[62:65], v[114:117], v[162:165], v[62:65]
	v_mfma_f32_16x16x32_bf16 v[58:61], v[126:129], v[162:165], v[58:61]
	v_mfma_f32_16x16x32_bf16 v[46:49], v[114:117], v[170:173], v[46:49]
	v_mfma_f32_16x16x32_bf16 v[42:45], v[126:129], v[170:173], v[42:45]
	v_mfma_f32_16x16x32_bf16 v[30:33], v[114:117], v[178:181], v[30:33]
	v_mfma_f32_16x16x32_bf16 v[26:29], v[126:129], v[178:181], v[26:29]
	v_mfma_f32_16x16x32_bf16 v[14:17], v[114:117], v[186:189], v[14:17]
	v_mfma_f32_16x16x32_bf16 v[10:13], v[126:129], v[186:189], v[10:13]
	v_mfma_f32_16x16x32_bf16 v[62:65], v[122:125], v[166:169], v[62:65]
	v_mfma_f32_16x16x32_bf16 v[58:61], v[130:133], v[166:169], v[58:61]
	v_mfma_f32_16x16x32_bf16 v[46:49], v[122:125], v[174:177], v[46:49]
	v_mfma_f32_16x16x32_bf16 v[42:45], v[130:133], v[174:177], v[42:45]
	v_mfma_f32_16x16x32_bf16 v[30:33], v[122:125], v[182:185], v[30:33]
	v_mfma_f32_16x16x32_bf16 v[26:29], v[130:133], v[182:185], v[26:29]
	v_mfma_f32_16x16x32_bf16 v[14:17], v[122:125], v[190:193], v[14:17]
	v_mfma_f32_16x16x32_bf16 v[10:13], v[130:133], v[190:193], v[10:13]
	s_setprio 0
	s_setprio 1
	v_mfma_f32_16x16x32_bf16 v[54:57], v[138:141], v[162:165], v[54:57]
	v_mfma_f32_16x16x32_bf16 v[50:53], v[146:149], v[162:165], v[50:53]
	v_mfma_f32_16x16x32_bf16 v[38:41], v[138:141], v[170:173], v[38:41]
	v_mfma_f32_16x16x32_bf16 v[34:37], v[146:149], v[170:173], v[34:37]
	v_mfma_f32_16x16x32_bf16 v[22:25], v[138:141], v[178:181], v[22:25]
	v_mfma_f32_16x16x32_bf16 v[18:21], v[146:149], v[178:181], v[18:21]
	v_mfma_f32_16x16x32_bf16 v[6:9], v[138:141], v[186:189], v[6:9]
	v_mfma_f32_16x16x32_bf16 v[2:5], v[146:149], v[186:189], v[2:5]
	v_mfma_f32_16x16x32_bf16 v[54:57], v[142:145], v[166:169], v[54:57]
	v_mfma_f32_16x16x32_bf16 v[50:53], v[158:161], v[166:169], v[50:53]
	v_mfma_f32_16x16x32_bf16 v[38:41], v[142:145], v[174:177], v[38:41]
	v_mfma_f32_16x16x32_bf16 v[34:37], v[158:161], v[174:177], v[34:37]
	v_mfma_f32_16x16x32_bf16 v[22:25], v[142:145], v[182:185], v[22:25]
	v_mfma_f32_16x16x32_bf16 v[18:21], v[158:161], v[182:185], v[18:21]
	v_mfma_f32_16x16x32_bf16 v[6:9], v[142:145], v[190:193], v[6:9]
	v_mfma_f32_16x16x32_bf16 v[2:5], v[158:161], v[190:193], v[2:5]
	s_setprio 0
	s_barrier
	s_add_i32 s66, 0, 0x18000
	s_add_i32 s77, 0, 0x1c000
	v_add_u32_e32 v130, s66, v252
	v_add_u32_e32 v158, s77, v252
	ds_read_b128 v[114:117], v130
	ds_read_b128 v[122:125], v130 offset:1024
	ds_read_b128 v[126:129], v130 offset:2048
	ds_read_b128 v[130:133], v130 offset:3072
	ds_read_b128 v[138:141], v158
	ds_read_b128 v[142:145], v158 offset:1024
	ds_read_b128 v[146:149], v158 offset:2048
	ds_read_b128 v[158:161], v158 offset:3072
	s_add_u32 s88, s88, s76
	s_addc_u32 s89, s89, 0
	s_mov_b32 m0, s27
	v_lshl_add_u64 v[218:219], s[88:89], 0, v[194:195]
	ds_read_b128 v[162:165], v254 offset:32768
	ds_read_b128 v[166:169], v254 offset:33792
	ds_read_b128 v[170:173], v254 offset:34816
	ds_read_b128 v[174:177], v254 offset:35840
	ds_read_b128 v[178:181], v254 offset:36864
	ds_read_b128 v[182:185], v254 offset:37888
	ds_read_b128 v[186:189], v254 offset:38912
	ds_read_b128 v[190:193], v254 offset:39936
	global_load_lds_dwordx4 v[218:219], off
	s_mov_b32 m0, s28
	v_lshl_add_u64 v[218:219], s[88:89], 0, v[196:197]
	global_load_lds_dwordx4 v[218:219], off
	s_waitcnt vmcnt(8)
	s_waitcnt lgkmcnt(0)
	s_barrier
	s_setprio 1
	s_waitcnt lgkmcnt(0)
	v_mfma_f32_16x16x32_bf16 v[154:157], v[114:117], v[162:165], v[154:157]
	v_mfma_f32_16x16x32_bf16 v[150:153], v[126:129], v[162:165], v[150:153]
	v_mfma_f32_16x16x32_bf16 v[110:113], v[114:117], v[170:173], v[110:113]
	v_mfma_f32_16x16x32_bf16 v[106:109], v[126:129], v[170:173], v[106:109]
	v_mfma_f32_16x16x32_bf16 v[94:97], v[114:117], v[178:181], v[94:97]
	v_mfma_f32_16x16x32_bf16 v[90:93], v[126:129], v[178:181], v[90:93]
	v_mfma_f32_16x16x32_bf16 v[78:81], v[114:117], v[186:189], v[78:81]
	v_mfma_f32_16x16x32_bf16 v[74:77], v[126:129], v[186:189], v[74:77]
	v_mfma_f32_16x16x32_bf16 v[154:157], v[122:125], v[166:169], v[154:157]
	v_mfma_f32_16x16x32_bf16 v[150:153], v[130:133], v[166:169], v[150:153]
	v_mfma_f32_16x16x32_bf16 v[110:113], v[122:125], v[174:177], v[110:113]
	v_mfma_f32_16x16x32_bf16 v[106:109], v[130:133], v[174:177], v[106:109]
	v_mfma_f32_16x16x32_bf16 v[94:97], v[122:125], v[182:185], v[94:97]
	v_mfma_f32_16x16x32_bf16 v[90:93], v[130:133], v[182:185], v[90:93]
	v_mfma_f32_16x16x32_bf16 v[78:81], v[122:125], v[190:193], v[78:81]
	v_mfma_f32_16x16x32_bf16 v[74:77], v[130:133], v[190:193], v[74:77]
	s_setprio 0
	s_setprio 1
	v_mfma_f32_16x16x32_bf16 v[134:137], v[138:141], v[162:165], v[134:137]
	v_mfma_f32_16x16x32_bf16 v[118:121], v[146:149], v[162:165], v[118:121]
	v_mfma_f32_16x16x32_bf16 v[102:105], v[138:141], v[170:173], v[102:105]
	v_mfma_f32_16x16x32_bf16 v[98:101], v[146:149], v[170:173], v[98:101]
	v_mfma_f32_16x16x32_bf16 v[86:89], v[138:141], v[178:181], v[86:89]
	v_mfma_f32_16x16x32_bf16 v[82:85], v[146:149], v[178:181], v[82:85]
	v_mfma_f32_16x16x32_bf16 v[70:73], v[138:141], v[186:189], v[70:73]
	v_mfma_f32_16x16x32_bf16 v[66:69], v[146:149], v[186:189], v[66:69]
	v_mfma_f32_16x16x32_bf16 v[134:137], v[142:145], v[166:169], v[134:137]
	v_mfma_f32_16x16x32_bf16 v[118:121], v[158:161], v[166:169], v[118:121]
	v_mfma_f32_16x16x32_bf16 v[102:105], v[142:145], v[174:177], v[102:105]
	v_mfma_f32_16x16x32_bf16 v[98:101], v[158:161], v[174:177], v[98:101]
	v_mfma_f32_16x16x32_bf16 v[86:89], v[142:145], v[182:185], v[86:89]
	v_mfma_f32_16x16x32_bf16 v[82:85], v[158:161], v[182:185], v[82:85]
	v_mfma_f32_16x16x32_bf16 v[70:73], v[142:145], v[190:193], v[70:73]
	v_mfma_f32_16x16x32_bf16 v[66:69], v[158:161], v[190:193], v[66:69]
	s_setprio 0
	s_barrier
; #define PG8_STAGE(bufoff, gbase, voff) do { _Pragma("unroll") for (int _i = 0; _i < 2; ++_i) \
;         __builtin_amdgcn_global_load_lds((const unsigned*)((const char*)(gbase) + (voff)[_i]), (PG8_LAS unsigned*)(lds + (bufoff) + ldsw + _i * 8192), 16, 0, 0); } while (0)
; #define PG8_LDA(dst, b, h) do { _Pragma("unroll") for (int m = 0; m < 4; ++m) _Pragma("unroll") for (int k = 0; k < 2; ++k) dst[m][k] = *(const PG8_LAS bf16x8*)(lds + PG8_SA(b, h) + aoff + m * 2048 + k * 1024); } while (0)
; #define PG8_MMA(ai, bj, At, Bt) do { __builtin_amdgcn_s_setprio(1); _Pragma("unroll") for (int m = 0; m < 4; ++m) _Pragma("unroll") for (int n = 0; n < 2; ++n) _Pragma("unroll") for (int k = 0; k < 2; ++k) \
;         acc[ai][bj][m][n] = __builtin_amdgcn_mfma_f32_16x16x32_bf16(Bt[n][k], At[m][k], acc[ai][bj][m][n], 0, 0, 0); __builtin_amdgcn_s_setprio(0); } while (0)
; #define PG8_WAIT_V(n) asm volatile("s_waitcnt vmcnt(" #n ")" ::: "memory")
; #define PG8_WAIT_L(n) asm volatile("s_waitcnt lgkmcnt(" #n ")" ::: "memory")
; #define PG8_BAR __builtin_amdgcn_s_barrier()
; #define PG8_SCHED __builtin_amdgcn_sched_barrier(0)
; template <class Epi, class Sched, bool ALIGN_EPI = false, bool SP2 = false>
; __device__ __forceinline__ void gemm_phase(PG8_LAS unsigned char* lds, const Gemm g, const Sched& S, const Epi& E) {
;     ...
;             PG8_LDA(At, 1, 1); PG8_STAGE(PG8_SB(1, 0), b3, voffB); PG8_STAGE(PG8_SB(1, 1), b3 + hstep, voffB); PG8_STAGE(PG8_SA(1, 0), a3, voffA);
;             PG8_WAIT_V(8); PG8_WAIT_L(0); PG8_BAR; PG8_MMA(1, 0, At, B0); PG8_MMA(1, 1, At, B1); PG8_BAR; PG8_SCHED;
	s_add_i32 s66, s66, s15
	v_lshl_add_u64 v[204:205], v[204:205], 0, s[24:25]
	s_mov_b32 m0, s66
	ds_read_b128 v[162:165], v254 offset:49152
	ds_read_b128 v[166:169], v254 offset:50176
	ds_read_b128 v[170:173], v254 offset:51200
	ds_read_b128 v[174:177], v254 offset:52224
	ds_read_b128 v[178:181], v254 offset:53248
	ds_read_b128 v[182:185], v254 offset:54272
	ds_read_b128 v[186:189], v254 offset:55296
	ds_read_b128 v[190:193], v254 offset:56320
	global_load_lds_dwordx4 v[204:205], off
	v_lshl_add_u64 v[204:205], v[208:209], 0, s[24:25]
	s_add_i32 m0, s66, 0x2000
	s_add_i32 s66, s77, s15
	global_load_lds_dwordx4 v[204:205], off
	s_mov_b32 m0, s66
	v_lshl_add_u64 v[204:205], v[210:211], 0, s[24:25]
	global_load_lds_dwordx4 v[204:205], off
	s_add_i32 m0, s66, 0x2000
	v_lshl_add_u64 v[204:205], v[212:213], 0, s[24:25]
	global_load_lds_dwordx4 v[204:205], off
	s_mov_b32 m0, s43
	v_lshl_add_u64 v[204:205], v[214:215], 0, s[24:25]
	global_load_lds_dwordx4 v[204:205], off
	s_mov_b32 m0, s44
	v_lshl_add_u64 v[204:205], v[216:217], 0, s[24:25]
	global_load_lds_dwordx4 v[204:205], off
	s_waitcnt vmcnt(8)
	s_waitcnt lgkmcnt(0)
	s_barrier
	s_setprio 1
	s_waitcnt lgkmcnt(0)
	v_mfma_f32_16x16x32_bf16 v[62:65], v[114:117], v[162:165], v[62:65]
	v_mfma_f32_16x16x32_bf16 v[58:61], v[126:129], v[162:165], v[58:61]
	v_mfma_f32_16x16x32_bf16 v[46:49], v[114:117], v[170:173], v[46:49]
	v_mfma_f32_16x16x32_bf16 v[42:45], v[126:129], v[170:173], v[42:45]
	v_mfma_f32_16x16x32_bf16 v[30:33], v[114:117], v[178:181], v[30:33]
	v_mfma_f32_16x16x32_bf16 v[26:29], v[126:129], v[178:181], v[26:29]
	v_mfma_f32_16x16x32_bf16 v[14:17], v[114:117], v[186:189], v[14:17]
	v_mfma_f32_16x16x32_bf16 v[10:13], v[126:129], v[186:189], v[10:13]
	v_mfma_f32_16x16x32_bf16 v[62:65], v[122:125], v[166:169], v[62:65]
	v_mfma_f32_16x16x32_bf16 v[58:61], v[130:133], v[166:169], v[58:61]
	v_mfma_f32_16x16x32_bf16 v[46:49], v[122:125], v[174:177], v[46:49]
	v_mfma_f32_16x16x32_bf16 v[42:45], v[130:133], v[174:177], v[42:45]
	v_mfma_f32_16x16x32_bf16 v[30:33], v[122:125], v[182:185], v[30:33]
	v_mfma_f32_16x16x32_bf16 v[26:29], v[130:133], v[182:185], v[26:29]
	v_mfma_f32_16x16x32_bf16 v[14:17], v[122:125], v[190:193], v[14:17]
	v_mfma_f32_16x16x32_bf16 v[10:13], v[130:133], v[190:193], v[10:13]
	s_setprio 0
	s_setprio 1
	v_mfma_f32_16x16x32_bf16 v[54:57], v[138:141], v[162:165], v[54:57]
	v_mfma_f32_16x16x32_bf16 v[50:53], v[146:149], v[162:165], v[50:53]
	v_mfma_f32_16x16x32_bf16 v[38:41], v[138:141], v[170:173], v[38:41]
	v_mfma_f32_16x16x32_bf16 v[34:37], v[146:149], v[170:173], v[34:37]
	v_mfma_f32_16x16x32_bf16 v[22:25], v[138:141], v[178:181], v[22:25]
	v_mfma_f32_16x16x32_bf16 v[18:21], v[146:149], v[178:181], v[18:21]
	v_mfma_f32_16x16x32_bf16 v[6:9], v[138:141], v[186:189], v[6:9]
	v_mfma_f32_16x16x32_bf16 v[2:5], v[146:149], v[186:189], v[2:5]
	v_mfma_f32_16x16x32_bf16 v[54:57], v[142:145], v[166:169], v[54:57]
	v_mfma_f32_16x16x32_bf16 v[50:53], v[158:161], v[166:169], v[50:53]
	v_mfma_f32_16x16x32_bf16 v[38:41], v[142:145], v[174:177], v[38:41]
	v_mfma_f32_16x16x32_bf16 v[34:37], v[158:161], v[174:177], v[34:37]
	v_mfma_f32_16x16x32_bf16 v[22:25], v[142:145], v[182:185], v[22:25]
	v_mfma_f32_16x16x32_bf16 v[18:21], v[158:161], v[182:185], v[18:21]
	v_mfma_f32_16x16x32_bf16 v[6:9], v[142:145], v[190:193], v[6:9]
	v_mfma_f32_16x16x32_bf16 v[2:5], v[158:161], v[190:193], v[2:5]
	s_setprio 0
	s_barrier
	s_add_u32 s86, s86, 0x100
	s_addc_u32 s87, s87, 0
	s_add_u32 s64, s64, 0x100
	s_addc_u32 s65, s65, 0
	s_cmp_ge_u32 s67, s42
	s_mov_b32 s66, s67
	s_cbranch_scc0 .LBB0_320
	s_and_b64 vcc, exec, s[82:83]
	s_cbranch_vccz .LBB0_323
	s_barrier

; #define PG8_STAGE(bufoff, gbase, voff) do { _Pragma("unroll") for (int _i = 0; _i < 2; ++_i) \
;         __builtin_amdgcn_global_load_lds((const unsigned*)((const char*)(gbase) + (voff)[_i]), (PG8_LAS unsigned*)(lds + (bufoff) + ldsw + _i * 8192), 16, 0, 0); } while (0)
; #define PG8_LDA(dst, b, h) do { _Pragma("unroll") for (int m = 0; m < 4; ++m) _Pragma("unroll") for (int k = 0; k < 2; ++k) dst[m][k] = *(const PG8_LAS bf16x8*)(lds + PG8_SA(b, h) + aoff + m * 2048 + k * 1024); } while (0)
; #define PG8_LDB(dst, b, h) do { _Pragma("unroll") for (int n = 0; n < 2; ++n) _Pragma("unroll") for (int k = 0; k < 2; ++k) dst[n][k] = *(const PG8_LAS bf16x8*)(lds + PG8_SB(b, h) + boff + n * 2048 + k * 1024); } while (0)
; #define PG8_MMA(ai, bj, At, Bt) do { __builtin_amdgcn_s_setprio(1); _Pragma("unroll") for (int m = 0; m < 4; ++m) _Pragma("unroll") for (int n = 0; n < 2; ++n) _Pragma("unroll") for (int k = 0; k < 2; ++k) \
;         acc[ai][bj][m][n] = __builtin_amdgcn_mfma_f32_16x16x32_bf16(Bt[n][k], At[m][k], acc[ai][bj][m][n], 0, 0, 0); __builtin_amdgcn_s_setprio(0); } while (0)
; #define PG8_WAIT_V(n) asm volatile("s_waitcnt vmcnt(" #n ")" ::: "memory")
; #define PG8_BAR __builtin_amdgcn_s_barrier()
; template <class Epi, class Sched, bool ALIGN_EPI = false, bool SP2 = false>
; __device__ __forceinline__ void gemm_phase(PG8_LAS unsigned char* lds, const Gemm g, const Sched& S, const Epi& E) {
;     ...
;         for (int t = 0; t < nt; t += 2) {
;             const bool last = (t == nt - 2);
;             const char* a1 = cA + (size_t)(t + 1) * kstep;
;             const char* a2 = last ? nA : cA + (size_t)(t + 2) * kstep; const char* b2 = last ? nB : cB + (size_t)(t + 2) * kstep;
;             const char* a3 = a2 + kstep; const char* b3 = b2 + kstep;
;             if (last && has_next) S.a_ready(nxt);
;             if constexpr (SP2) {
;             PG8_LDB(B0, 0, 0); PG8_LDB(B1, 0, 1); PG8_SCHED; PG8_LDA(At, 0, 0); PG8_STAGE(PG8_SA(1, 1), a1 + hstep, voffA);
;             PG8_WAIT_V(8); PG8_WAIT_L(0); PG8_BAR; PG8_MMA(0, 0, At, B0); PG8_MMA(0, 1, At, B1); PG8_BAR; PG8_SCHED;
;             PG8_LDA(At, 0, 1); PG8_STAGE(PG8_SB(0, 0), b2, voffB); PG8_STAGE(PG8_SB(0, 1), b2 + hstep, voffB); PG8_STAGE(PG8_SA(0, 0), a2, voffA);
;             PG8_WAIT_V(8); PG8_WAIT_L(0); PG8_BAR; PG8_MMA(1, 0, At, B0); PG8_MMA(1, 1, At, B1); PG8_BAR; PG8_SCHED;
.LBB0_468:
	s_add_u32 s82, s80, 0xfffc0080
	s_addc_u32 s83, s81, -1
	s_add_i32 s97, 0, 0x10000
	s_cmp_eq_u32 s96, 12
	s_cselect_b32 s85, s75, s83
	s_cselect_b32 s84, s92, s82
	v_add_u32_e32 v140, s97, v143
	s_cselect_b32 s83, s73, s95
	s_cselect_b32 s82, s93, s94
	s_add_i32 vcc_lo, 0, 0x14000
	ds_read_b128 v[146:149], v140
	ds_read_b128 v[150:153], v140 offset:1024
	ds_read_b128 v[154:157], v140 offset:2048
	ds_read_b128 v[158:161], v140 offset:3072
	v_add_u32_e32 v140, vcc_lo, v143
	ds_read_b128 v[162:165], v140
	ds_read_b128 v[166:169], v140 offset:1024
	ds_read_b128 v[170:173], v140 offset:2048
	ds_read_b128 v[174:177], v140 offset:3072
	v_lshl_add_u64 v[140:141], s[80:81], 0, v[136:137]
	s_add_i32 m0, s49, 0xc000
	ds_read_b128 v[178:181], v145
	ds_read_b128 v[182:185], v145 offset:1024
	ds_read_b128 v[186:189], v145 offset:2048
	ds_read_b128 v[190:193], v145 offset:3072
	ds_read_b128 v[194:197], v145 offset:4096
	ds_read_b128 v[198:201], v145 offset:5120
	ds_read_b128 v[202:205], v145 offset:6144
	ds_read_b128 v[212:215], v145 offset:7168
	global_load_lds_dwordx4 v[140:141], off
	s_add_i32 m0, s49, 0xe000
	v_lshl_add_u64 v[140:141], s[80:81], 0, v[138:139]
	global_load_lds_dwordx4 v[140:141], off
	s_waitcnt vmcnt(8)
	s_waitcnt lgkmcnt(0)
	s_barrier
	s_setprio 1
	s_waitcnt lgkmcnt(0)
	v_mfma_f32_16x16x32_bf16 v[126:129], v[146:149], v[178:181], v[126:129]
	v_mfma_f32_16x16x32_bf16 v[122:125], v[154:157], v[178:181], v[122:125]
	v_mfma_f32_16x16x32_bf16 v[118:121], v[146:149], v[186:189], v[118:121]
	v_mfma_f32_16x16x32_bf16 v[110:113], v[154:157], v[186:189], v[110:113]
	v_mfma_f32_16x16x32_bf16 v[102:105], v[146:149], v[194:197], v[102:105]
	v_mfma_f32_16x16x32_bf16 v[94:97], v[154:157], v[194:197], v[94:97]
	v_mfma_f32_16x16x32_bf16 v[86:89], v[146:149], v[202:205], v[86:89]
	v_mfma_f32_16x16x32_bf16 v[78:81], v[154:157], v[202:205], v[78:81]
	v_mfma_f32_16x16x32_bf16 v[126:129], v[150:153], v[182:185], v[126:129]
	v_mfma_f32_16x16x32_bf16 v[122:125], v[158:161], v[182:185], v[122:125]
	v_mfma_f32_16x16x32_bf16 v[118:121], v[150:153], v[190:193], v[118:121]
	v_mfma_f32_16x16x32_bf16 v[110:113], v[158:161], v[190:193], v[110:113]
	v_mfma_f32_16x16x32_bf16 v[102:105], v[150:153], v[198:201], v[102:105]
	v_mfma_f32_16x16x32_bf16 v[94:97], v[158:161], v[198:201], v[94:97]
	v_mfma_f32_16x16x32_bf16 v[86:89], v[150:153], v[212:215], v[86:89]
	v_mfma_f32_16x16x32_bf16 v[78:81], v[158:161], v[212:215], v[78:81]
	s_setprio 0
	s_setprio 1
	v_mfma_f32_16x16x32_bf16 v[114:117], v[162:165], v[178:181], v[114:117]
	v_mfma_f32_16x16x32_bf16 v[106:109], v[170:173], v[178:181], v[106:109]
	v_mfma_f32_16x16x32_bf16 v[98:101], v[162:165], v[186:189], v[98:101]
	v_mfma_f32_16x16x32_bf16 v[90:93], v[170:173], v[186:189], v[90:93]
	v_mfma_f32_16x16x32_bf16 v[82:85], v[162:165], v[194:197], v[82:85]
	v_mfma_f32_16x16x32_bf16 v[74:77], v[170:173], v[194:197], v[74:77]
	v_mfma_f32_16x16x32_bf16 v[70:73], v[162:165], v[202:205], v[70:73]
	v_mfma_f32_16x16x32_bf16 v[66:69], v[170:173], v[202:205], v[66:69]
	v_mfma_f32_16x16x32_bf16 v[114:117], v[166:169], v[182:185], v[114:117]
	v_mfma_f32_16x16x32_bf16 v[106:109], v[174:177], v[182:185], v[106:109]
	v_mfma_f32_16x16x32_bf16 v[98:101], v[166:169], v[190:193], v[98:101]
	v_mfma_f32_16x16x32_bf16 v[90:93], v[174:177], v[190:193], v[90:93]
	v_mfma_f32_16x16x32_bf16 v[82:85], v[166:169], v[198:201], v[82:85]
	v_mfma_f32_16x16x32_bf16 v[74:77], v[174:177], v[198:201], v[74:77]
	v_mfma_f32_16x16x32_bf16 v[70:73], v[166:169], v[212:215], v[70:73]
	v_mfma_f32_16x16x32_bf16 v[66:69], v[174:177], v[212:215], v[66:69]
	s_setprio 0
	s_barrier
	s_add_i32 s97, s97, s47
	v_lshl_add_u64 v[140:141], s[82:83], 0, v[0:1]
	s_mov_b32 m0, s97
	ds_read_b128 v[178:181], v145 offset:16384
	ds_read_b128 v[182:185], v145 offset:17408
	ds_read_b128 v[186:189], v145 offset:18432
	ds_read_b128 v[190:193], v145 offset:19456
	ds_read_b128 v[194:197], v145 offset:20480
	ds_read_b128 v[198:201], v145 offset:21504
	ds_read_b128 v[202:205], v145 offset:22528
	ds_read_b128 v[212:215], v145 offset:23552
	global_load_lds_dwordx4 v[140:141], off
	s_add_i32 m0, s97, 0x2000
	s_add_u32 s98, s82, 0x40000
	v_lshl_add_u64 v[208:209], s[82:83], 0, v[130:131]
	s_addc_u32 s99, s83, 0
	s_add_i32 s97, vcc_lo, s47
	global_load_lds_dwordx4 v[208:209], off
	v_lshl_add_u64 v[210:211], s[98:99], 0, v[0:1]
	s_mov_b32 m0, s97
	v_lshl_add_u64 v[216:217], s[84:85], 0, v[132:133]
	global_load_lds_dwordx4 v[210:211], off
	s_add_i32 m0, s97, 0x2000
	v_lshl_add_u64 v[210:211], s[98:99], 0, v[130:131]
	global_load_lds_dwordx4 v[210:211], off
	s_mov_b32 m0, s49
	v_lshl_add_u64 v[210:211], s[84:85], 0, v[134:135]
	global_load_lds_dwordx4 v[210:211], off
	s_mov_b32 m0, s54
	s_nop 0
	global_load_lds_dwordx4 v[216:217], off
	s_waitcnt vmcnt(8)
	s_waitcnt lgkmcnt(0)
	s_barrier
; #define PG8_STAGE(bufoff, gbase, voff) do { _Pragma("unroll") for (int _i = 0; _i < 2; ++_i) \
;         __builtin_amdgcn_global_load_lds((const unsigned*)((const char*)(gbase) + (voff)[_i]), (PG8_LAS unsigned*)(lds + (bufoff) + ldsw + _i * 8192), 16, 0, 0); } while (0)
; #define PG8_LDA(dst, b, h) do { _Pragma("unroll") for (int m = 0; m < 4; ++m) _Pragma("unroll") for (int k = 0; k < 2; ++k) dst[m][k] = *(const PG8_LAS bf16x8*)(lds + PG8_SA(b, h) + aoff + m * 2048 + k * 1024); } while (0)
; #define PG8_LDB(dst, b, h) do { _Pragma("unroll") for (int n = 0; n < 2; ++n) _Pragma("unroll") for (int k = 0; k < 2; ++k) dst[n][k] = *(const PG8_LAS bf16x8*)(lds + PG8_SB(b, h) + boff + n * 2048 + k * 1024); } while (0)
; #define PG8_MMA(ai, bj, At, Bt) do { __builtin_amdgcn_s_setprio(1); _Pragma("unroll") for (int m = 0; m < 4; ++m) _Pragma("unroll") for (int n = 0; n < 2; ++n) _Pragma("unroll") for (int k = 0; k < 2; ++k) \
;         acc[ai][bj][m][n] = __builtin_amdgcn_mfma_f32_16x16x32_bf16(Bt[n][k], At[m][k], acc[ai][bj][m][n], 0, 0, 0); __builtin_amdgcn_s_setprio(0); } while (0)
; #define PG8_WAIT_V(n) asm volatile("s_waitcnt vmcnt(" #n ")" ::: "memory")
; #define PG8_WAIT_L(n) asm volatile("s_waitcnt lgkmcnt(" #n ")" ::: "memory")
; #define PG8_BAR __builtin_amdgcn_s_barrier()
; #define PG8_SCHED __builtin_amdgcn_sched_barrier(0)
; template <class Epi, class Sched, bool ALIGN_EPI = false, bool SP2 = false>
; __device__ __forceinline__ void gemm_phase(PG8_LAS unsigned char* lds, const Gemm g, const Sched& S, const Epi& E) {
;     ...
;             PG8_WAIT_V(8); PG8_WAIT_L(0); PG8_BAR; PG8_MMA(1, 0, At, B0); PG8_MMA(1, 1, At, B1); PG8_BAR; PG8_SCHED;
;             PG8_LDB(B0, 1, 0); PG8_LDB(B1, 1, 1); PG8_SCHED; PG8_LDA(At, 1, 0); PG8_STAGE(PG8_SA(0, 1), a2 + hstep, voffA);
;             PG8_WAIT_V(8); PG8_WAIT_L(0); PG8_BAR; PG8_MMA(0, 0, At, B0); PG8_MMA(0, 1, At, B1); PG8_BAR; PG8_SCHED;
	s_setprio 1
	s_waitcnt lgkmcnt(0)
	v_mfma_f32_16x16x32_bf16 v[62:65], v[146:149], v[178:181], v[62:65]
	v_mfma_f32_16x16x32_bf16 v[58:61], v[154:157], v[178:181], v[58:61]
	v_mfma_f32_16x16x32_bf16 v[54:57], v[146:149], v[186:189], v[54:57]
	v_mfma_f32_16x16x32_bf16 v[46:49], v[154:157], v[186:189], v[46:49]
	v_mfma_f32_16x16x32_bf16 v[38:41], v[146:149], v[194:197], v[38:41]
	v_mfma_f32_16x16x32_bf16 v[30:33], v[154:157], v[194:197], v[30:33]
	v_mfma_f32_16x16x32_bf16 v[22:25], v[146:149], v[202:205], v[22:25]
	v_mfma_f32_16x16x32_bf16 v[14:17], v[154:157], v[202:205], v[14:17]
	v_mfma_f32_16x16x32_bf16 v[62:65], v[150:153], v[182:185], v[62:65]
	v_mfma_f32_16x16x32_bf16 v[58:61], v[158:161], v[182:185], v[58:61]
	v_mfma_f32_16x16x32_bf16 v[54:57], v[150:153], v[190:193], v[54:57]
	v_mfma_f32_16x16x32_bf16 v[46:49], v[158:161], v[190:193], v[46:49]
	v_mfma_f32_16x16x32_bf16 v[38:41], v[150:153], v[198:201], v[38:41]
	v_mfma_f32_16x16x32_bf16 v[30:33], v[158:161], v[198:201], v[30:33]
	v_mfma_f32_16x16x32_bf16 v[22:25], v[150:153], v[212:215], v[22:25]
	v_mfma_f32_16x16x32_bf16 v[14:17], v[158:161], v[212:215], v[14:17]
	s_setprio 0
	s_setprio 1
	v_mfma_f32_16x16x32_bf16 v[50:53], v[162:165], v[178:181], v[50:53]
	v_mfma_f32_16x16x32_bf16 v[42:45], v[170:173], v[178:181], v[42:45]
	v_mfma_f32_16x16x32_bf16 v[34:37], v[162:165], v[186:189], v[34:37]
	v_mfma_f32_16x16x32_bf16 v[26:29], v[170:173], v[186:189], v[26:29]
	v_mfma_f32_16x16x32_bf16 v[18:21], v[162:165], v[194:197], v[18:21]
	v_mfma_f32_16x16x32_bf16 v[10:13], v[170:173], v[194:197], v[10:13]
	v_mfma_f32_16x16x32_bf16 v[6:9], v[162:165], v[202:205], v[6:9]
	v_mfma_f32_16x16x32_bf16 v[2:5], v[170:173], v[202:205], v[2:5]
	v_mfma_f32_16x16x32_bf16 v[50:53], v[166:169], v[182:185], v[50:53]
	v_mfma_f32_16x16x32_bf16 v[42:45], v[174:177], v[182:185], v[42:45]
	v_mfma_f32_16x16x32_bf16 v[34:37], v[166:169], v[190:193], v[34:37]
	v_mfma_f32_16x16x32_bf16 v[26:29], v[174:177], v[190:193], v[26:29]
	v_mfma_f32_16x16x32_bf16 v[18:21], v[166:169], v[198:201], v[18:21]
	v_mfma_f32_16x16x32_bf16 v[10:13], v[174:177], v[198:201], v[10:13]
	v_mfma_f32_16x16x32_bf16 v[6:9], v[166:169], v[212:215], v[6:9]
	v_mfma_f32_16x16x32_bf16 v[2:5], v[174:177], v[212:215], v[2:5]
	s_setprio 0
	s_barrier
	s_add_i32 s97, 0, 0x18000
	s_add_i32 s98, 0, 0x1c000
	v_add_u32_e32 v158, s97, v143
	v_add_u32_e32 v174, s98, v143
	ds_read_b128 v[146:149], v158
	ds_read_b128 v[150:153], v158 offset:1024
	ds_read_b128 v[154:157], v158 offset:2048
	ds_read_b128 v[158:161], v158 offset:3072
	ds_read_b128 v[162:165], v174
	ds_read_b128 v[166:169], v174 offset:1024
	ds_read_b128 v[170:173], v174 offset:2048
	ds_read_b128 v[174:177], v174 offset:3072
	s_add_u32 s84, s84, 0x40000
	s_addc_u32 s85, s85, 0
	s_mov_b32 m0, s55
	v_lshl_add_u64 v[218:219], s[84:85], 0, v[134:135]
	ds_read_b128 v[178:181], v145 offset:32768
	ds_read_b128 v[182:185], v145 offset:33792
	ds_read_b128 v[186:189], v145 offset:34816
	ds_read_b128 v[190:193], v145 offset:35840
	ds_read_b128 v[194:197], v145 offset:36864
	ds_read_b128 v[198:201], v145 offset:37888
	ds_read_b128 v[202:205], v145 offset:38912
	ds_read_b128 v[212:215], v145 offset:39936
	global_load_lds_dwordx4 v[218:219], off
	s_mov_b32 m0, s66
	v_lshl_add_u64 v[218:219], s[84:85], 0, v[132:133]
	global_load_lds_dwordx4 v[218:219], off
	s_waitcnt vmcnt(8)
	s_waitcnt lgkmcnt(0)
	s_barrier
	s_setprio 1
	s_waitcnt lgkmcnt(0)
	v_mfma_f32_16x16x32_bf16 v[126:129], v[146:149], v[178:181], v[126:129]
	v_mfma_f32_16x16x32_bf16 v[122:125], v[154:157], v[178:181], v[122:125]
	v_mfma_f32_16x16x32_bf16 v[118:121], v[146:149], v[186:189], v[118:121]
	v_mfma_f32_16x16x32_bf16 v[110:113], v[154:157], v[186:189], v[110:113]
	v_mfma_f32_16x16x32_bf16 v[102:105], v[146:149], v[194:197], v[102:105]
	v_mfma_f32_16x16x32_bf16 v[94:97], v[154:157], v[194:197], v[94:97]
	v_mfma_f32_16x16x32_bf16 v[86:89], v[146:149], v[202:205], v[86:89]
	v_mfma_f32_16x16x32_bf16 v[78:81], v[154:157], v[202:205], v[78:81]
	v_mfma_f32_16x16x32_bf16 v[126:129], v[150:153], v[182:185], v[126:129]
	v_mfma_f32_16x16x32_bf16 v[122:125], v[158:161], v[182:185], v[122:125]
	v_mfma_f32_16x16x32_bf16 v[118:121], v[150:153], v[190:193], v[118:121]
	v_mfma_f32_16x16x32_bf16 v[110:113], v[158:161], v[190:193], v[110:113]
	v_mfma_f32_16x16x32_bf16 v[102:105], v[150:153], v[198:201], v[102:105]
	v_mfma_f32_16x16x32_bf16 v[94:97], v[158:161], v[198:201], v[94:97]
	v_mfma_f32_16x16x32_bf16 v[86:89], v[150:153], v[212:215], v[86:89]
	v_mfma_f32_16x16x32_bf16 v[78:81], v[158:161], v[212:215], v[78:81]
	s_setprio 0
	s_setprio 1
	v_mfma_f32_16x16x32_bf16 v[114:117], v[162:165], v[178:181], v[114:117]
	v_mfma_f32_16x16x32_bf16 v[106:109], v[170:173], v[178:181], v[106:109]
	v_mfma_f32_16x16x32_bf16 v[98:101], v[162:165], v[186:189], v[98:101]
	v_mfma_f32_16x16x32_bf16 v[90:93], v[170:173], v[186:189], v[90:93]
	v_mfma_f32_16x16x32_bf16 v[82:85], v[162:165], v[194:197], v[82:85]
	v_mfma_f32_16x16x32_bf16 v[74:77], v[170:173], v[194:197], v[74:77]
	v_mfma_f32_16x16x32_bf16 v[70:73], v[162:165], v[202:205], v[70:73]
	v_mfma_f32_16x16x32_bf16 v[66:69], v[170:173], v[202:205], v[66:69]
	v_mfma_f32_16x16x32_bf16 v[114:117], v[166:169], v[182:185], v[114:117]
	v_mfma_f32_16x16x32_bf16 v[106:109], v[174:177], v[182:185], v[106:109]
	v_mfma_f32_16x16x32_bf16 v[98:101], v[166:169], v[190:193], v[98:101]
	v_mfma_f32_16x16x32_bf16 v[90:93], v[174:177], v[190:193], v[90:93]
	v_mfma_f32_16x16x32_bf16 v[82:85], v[166:169], v[198:201], v[82:85]
	v_mfma_f32_16x16x32_bf16 v[74:77], v[174:177], v[198:201], v[74:77]
	v_mfma_f32_16x16x32_bf16 v[70:73], v[166:169], v[212:215], v[70:73]
	v_mfma_f32_16x16x32_bf16 v[66:69], v[174:177], v[212:215], v[66:69]
	s_setprio 0
	s_barrier
; #define PG8_STAGE(bufoff, gbase, voff) do { _Pragma("unroll") for (int _i = 0; _i < 2; ++_i) \
;         __builtin_amdgcn_global_load_lds((const unsigned*)((const char*)(gbase) + (voff)[_i]), (PG8_LAS unsigned*)(lds + (bufoff) + ldsw + _i * 8192), 16, 0, 0); } while (0)
; #define PG8_LDA(dst, b, h) do { _Pragma("unroll") for (int m = 0; m < 4; ++m) _Pragma("unroll") for (int k = 0; k < 2; ++k) dst[m][k] = *(const PG8_LAS bf16x8*)(lds + PG8_SA(b, h) + aoff + m * 2048 + k * 1024); } while (0)
; #define PG8_MMA(ai, bj, At, Bt) do { __builtin_amdgcn_s_setprio(1); _Pragma("unroll") for (int m = 0; m < 4; ++m) _Pragma("unroll") for (int n = 0; n < 2; ++n) _Pragma("unroll") for (int k = 0; k < 2; ++k) \
;         acc[ai][bj][m][n] = __builtin_amdgcn_mfma_f32_16x16x32_bf16(Bt[n][k], At[m][k], acc[ai][bj][m][n], 0, 0, 0); __builtin_amdgcn_s_setprio(0); } while (0)
; #define PG8_WAIT_V(n) asm volatile("s_waitcnt vmcnt(" #n ")" ::: "memory")
; #define PG8_WAIT_L(n) asm volatile("s_waitcnt lgkmcnt(" #n ")" ::: "memory")
; #define PG8_BAR __builtin_amdgcn_s_barrier()
; #define PG8_SCHED __builtin_amdgcn_sched_barrier(0)
; template <class Epi, class Sched, bool ALIGN_EPI = false, bool SP2 = false>
; __device__ __forceinline__ void gemm_phase(PG8_LAS unsigned char* lds, const Gemm g, const Sched& S, const Epi& E) {
;     ...
;             PG8_LDA(At, 1, 1); PG8_STAGE(PG8_SB(1, 0), b3, voffB); PG8_STAGE(PG8_SB(1, 1), b3 + hstep, voffB); PG8_STAGE(PG8_SA(1, 0), a3, voffA);
;             PG8_WAIT_V(8); PG8_WAIT_L(0); PG8_BAR; PG8_MMA(1, 0, At, B0); PG8_MMA(1, 1, At, B1); PG8_BAR; PG8_SCHED;
	s_add_i32 s84, s97, s47
	v_lshl_add_u64 v[140:141], v[140:141], 0, s[24:25]
	s_mov_b32 m0, s84
	ds_read_b128 v[178:181], v145 offset:49152
	ds_read_b128 v[182:185], v145 offset:50176
	ds_read_b128 v[186:189], v145 offset:51200
	ds_read_b128 v[190:193], v145 offset:52224
	ds_read_b128 v[194:197], v145 offset:53248
	ds_read_b128 v[198:201], v145 offset:54272
	ds_read_b128 v[202:205], v145 offset:55296
	ds_read_b128 v[212:215], v145 offset:56320
	global_load_lds_dwordx4 v[140:141], off
	s_add_i32 m0, s84, 0x2000
	s_add_u32 s82, s82, 0x40080
	v_lshl_add_u64 v[140:141], v[208:209], 0, s[24:25]
	s_addc_u32 s83, s83, 0
	s_add_i32 s84, s98, s47
	global_load_lds_dwordx4 v[140:141], off
	s_mov_b32 m0, s84
	v_lshl_add_u64 v[140:141], s[82:83], 0, v[0:1]
	global_load_lds_dwordx4 v[140:141], off
	s_add_i32 m0, s84, 0x2000
	v_lshl_add_u64 v[140:141], s[82:83], 0, v[130:131]
	global_load_lds_dwordx4 v[140:141], off
	s_mov_b32 m0, s67
	v_lshl_add_u64 v[140:141], v[210:211], 0, s[24:25]
	global_load_lds_dwordx4 v[140:141], off
	s_mov_b32 m0, s88
	v_lshl_add_u64 v[140:141], v[216:217], 0, s[24:25]
	global_load_lds_dwordx4 v[140:141], off
	s_waitcnt vmcnt(8)
	s_waitcnt lgkmcnt(0)
	s_barrier
	s_setprio 1
	s_waitcnt lgkmcnt(0)
	v_mfma_f32_16x16x32_bf16 v[62:65], v[146:149], v[178:181], v[62:65]
	v_mfma_f32_16x16x32_bf16 v[58:61], v[154:157], v[178:181], v[58:61]
	v_mfma_f32_16x16x32_bf16 v[54:57], v[146:149], v[186:189], v[54:57]
	v_mfma_f32_16x16x32_bf16 v[46:49], v[154:157], v[186:189], v[46:49]
	v_mfma_f32_16x16x32_bf16 v[38:41], v[146:149], v[194:197], v[38:41]
	v_mfma_f32_16x16x32_bf16 v[30:33], v[154:157], v[194:197], v[30:33]
	v_mfma_f32_16x16x32_bf16 v[22:25], v[146:149], v[202:205], v[22:25]
	v_mfma_f32_16x16x32_bf16 v[14:17], v[154:157], v[202:205], v[14:17]
	v_mfma_f32_16x16x32_bf16 v[62:65], v[150:153], v[182:185], v[62:65]
	v_mfma_f32_16x16x32_bf16 v[58:61], v[158:161], v[182:185], v[58:61]
	v_mfma_f32_16x16x32_bf16 v[54:57], v[150:153], v[190:193], v[54:57]
	v_mfma_f32_16x16x32_bf16 v[46:49], v[158:161], v[190:193], v[46:49]
	v_mfma_f32_16x16x32_bf16 v[38:41], v[150:153], v[198:201], v[38:41]
	v_mfma_f32_16x16x32_bf16 v[30:33], v[158:161], v[198:201], v[30:33]
	v_mfma_f32_16x16x32_bf16 v[22:25], v[150:153], v[212:215], v[22:25]
	v_mfma_f32_16x16x32_bf16 v[14:17], v[158:161], v[212:215], v[14:17]
	s_setprio 0
	s_setprio 1
	v_mfma_f32_16x16x32_bf16 v[50:53], v[162:165], v[178:181], v[50:53]
	v_mfma_f32_16x16x32_bf16 v[42:45], v[170:173], v[178:181], v[42:45]
	v_mfma_f32_16x16x32_bf16 v[34:37], v[162:165], v[186:189], v[34:37]
	v_mfma_f32_16x16x32_bf16 v[26:29], v[170:173], v[186:189], v[26:29]
	v_mfma_f32_16x16x32_bf16 v[18:21], v[162:165], v[194:197], v[18:21]
	v_mfma_f32_16x16x32_bf16 v[10:13], v[170:173], v[194:197], v[10:13]
	v_mfma_f32_16x16x32_bf16 v[6:9], v[162:165], v[202:205], v[6:9]
	v_mfma_f32_16x16x32_bf16 v[2:5], v[170:173], v[202:205], v[2:5]
	v_mfma_f32_16x16x32_bf16 v[50:53], v[166:169], v[182:185], v[50:53]
	v_mfma_f32_16x16x32_bf16 v[42:45], v[174:177], v[182:185], v[42:45]
	v_mfma_f32_16x16x32_bf16 v[34:37], v[166:169], v[190:193], v[34:37]
	v_mfma_f32_16x16x32_bf16 v[26:29], v[174:177], v[190:193], v[26:29]
	v_mfma_f32_16x16x32_bf16 v[18:21], v[166:169], v[198:201], v[18:21]
	v_mfma_f32_16x16x32_bf16 v[10:13], v[174:177], v[198:201], v[10:13]
	v_mfma_f32_16x16x32_bf16 v[6:9], v[166:169], v[212:215], v[6:9]
	v_mfma_f32_16x16x32_bf16 v[2:5], v[174:177], v[212:215], v[2:5]
	s_setprio 0
	s_barrier
	s_add_i32 s96, s96, 2
	s_add_u32 s80, s80, 0x100
	s_addc_u32 s81, s81, 0
	s_add_u32 s94, s94, 0x100
	s_addc_u32 s95, s95, 0
	s_cmp_gt_u32 s96, 13
	s_cbranch_scc0 .LBB0_468
	s_and_b64 vcc, exec, s[70:71]
	s_cbranch_vccz .LBB0_471
	s_barrier

; #define PG8_STAGE(bufoff, gbase, voff) do { _Pragma("unroll") for (int _i = 0; _i < 2; ++_i) \
;         __builtin_amdgcn_global_load_lds((const unsigned*)((const char*)(gbase) + (voff)[_i]), (PG8_LAS unsigned*)(lds + (bufoff) + ldsw + _i * 8192), 16, 0, 0); } while (0)
; #define PG8_LDA(dst, b, h) do { _Pragma("unroll") for (int m = 0; m < 4; ++m) _Pragma("unroll") for (int k = 0; k < 2; ++k) dst[m][k] = *(const PG8_LAS bf16x8*)(lds + PG8_SA(b, h) + aoff + m * 2048 + k * 1024); } while (0)
; #define PG8_LDB(dst, b, h) do { _Pragma("unroll") for (int n = 0; n < 2; ++n) _Pragma("unroll") for (int k = 0; k < 2; ++k) dst[n][k] = *(const PG8_LAS bf16x8*)(lds + PG8_SB(b, h) + boff + n * 2048 + k * 1024); } while (0)
; #define PG8_MMA(ai, bj, At, Bt) do { __builtin_amdgcn_s_setprio(1); _Pragma("unroll") for (int m = 0; m < 4; ++m) _Pragma("unroll") for (int n = 0; n < 2; ++n) _Pragma("unroll") for (int k = 0; k < 2; ++k) \
;         acc[ai][bj][m][n] = __builtin_amdgcn_mfma_f32_16x16x32_bf16(Bt[n][k], At[m][k], acc[ai][bj][m][n], 0, 0, 0); __builtin_amdgcn_s_setprio(0); } while (0)
; #define PG8_WAIT_V(n) asm volatile("s_waitcnt vmcnt(" #n ")" ::: "memory")
; #define PG8_BAR __builtin_amdgcn_s_barrier()
; template <class Epi, class Sched, bool ALIGN_EPI = false, bool SP2 = false>
; __device__ __forceinline__ void gemm_phase(PG8_LAS unsigned char* lds, const Gemm g, const Sched& S, const Epi& E) {
;     ...
;         for (int t = 0; t < nt; t += 2) {
;             const bool last = (t == nt - 2);
;             const char* a1 = cA + (size_t)(t + 1) * kstep;
;             const char* a2 = last ? nA : cA + (size_t)(t + 2) * kstep; const char* b2 = last ? nB : cB + (size_t)(t + 2) * kstep;
;             const char* a3 = a2 + kstep; const char* b3 = b2 + kstep;
;             if (last && has_next) S.a_ready(nxt);
;             if constexpr (SP2) {
;             PG8_LDB(B0, 0, 0); PG8_LDB(B1, 0, 1); PG8_SCHED; PG8_LDA(At, 0, 0); PG8_STAGE(PG8_SA(1, 1), a1 + hstep, voffA);
;             PG8_WAIT_V(8); PG8_WAIT_L(0); PG8_BAR; PG8_MMA(0, 0, At, B0); PG8_MMA(0, 1, At, B1); PG8_BAR; PG8_SCHED;
;             PG8_LDA(At, 0, 1); PG8_STAGE(PG8_SB(0, 0), b2, voffB); PG8_STAGE(PG8_SB(0, 1), b2 + hstep, voffB); PG8_STAGE(PG8_SA(0, 0), a2, voffA);
;             PG8_WAIT_V(8); PG8_WAIT_L(0); PG8_BAR; PG8_MMA(1, 0, At, B0); PG8_MMA(1, 1, At, B1); PG8_BAR; PG8_SCHED;
.LBB0_509:
	s_add_u32 s78, s76, 0xfffc0080
	s_addc_u32 s79, s77, -1
	s_add_i32 s89, 0, 0x10000
	s_cmp_eq_u32 s88, 12
	s_cselect_b32 s81, s69, s79
	s_cselect_b32 s80, s75, s78
	v_add_u32_e32 v0, s89, v149
	s_cselect_b32 s79, s67, s85
	s_cselect_b32 s78, s83, s84
	s_add_i32 s92, 0, 0x14000
	ds_read_b128 v[142:145], v0
	ds_read_b128 v[154:157], v0 offset:1024
	ds_read_b128 v[158:161], v0 offset:2048
	ds_read_b128 v[162:165], v0 offset:3072
	v_add_u32_e32 v0, s92, v149
	ds_read_b128 v[166:169], v0
	ds_read_b128 v[170:173], v0 offset:1024
	ds_read_b128 v[174:177], v0 offset:2048
	ds_read_b128 v[178:181], v0 offset:3072
	v_lshl_add_u64 v[208:209], s[76:77], 0, v[138:139]
	s_add_i32 m0, s7, 0xc000
	ds_read_b128 v[182:185], v152
	ds_read_b128 v[186:189], v152 offset:1024
	ds_read_b128 v[190:193], v152 offset:2048
	ds_read_b128 v[194:197], v152 offset:3072
	ds_read_b128 v[198:201], v152 offset:4096
	ds_read_b128 v[202:205], v152 offset:5120
	ds_read_b128 v[212:215], v152 offset:6144
	ds_read_b128 v[216:219], v152 offset:7168
	global_load_lds_dwordx4 v[208:209], off
	s_add_i32 m0, s7, 0xe000
	v_lshl_add_u64 v[208:209], s[76:77], 0, v[140:141]
	global_load_lds_dwordx4 v[208:209], off
	s_waitcnt vmcnt(8)
	s_waitcnt lgkmcnt(0)
	s_barrier
	s_setprio 1
	s_waitcnt lgkmcnt(0)
	v_mfma_f32_16x16x32_bf16 v[126:129], v[142:145], v[182:185], v[126:129]
	v_mfma_f32_16x16x32_bf16 v[122:125], v[158:161], v[182:185], v[122:125]
	v_mfma_f32_16x16x32_bf16 v[110:113], v[142:145], v[190:193], v[110:113]
	v_mfma_f32_16x16x32_bf16 v[106:109], v[158:161], v[190:193], v[106:109]
	v_mfma_f32_16x16x32_bf16 v[94:97], v[142:145], v[198:201], v[94:97]
	v_mfma_f32_16x16x32_bf16 v[90:93], v[158:161], v[198:201], v[90:93]
	v_mfma_f32_16x16x32_bf16 v[78:81], v[142:145], v[212:215], v[78:81]
	v_mfma_f32_16x16x32_bf16 v[74:77], v[158:161], v[212:215], v[74:77]
	v_mfma_f32_16x16x32_bf16 v[126:129], v[154:157], v[186:189], v[126:129]
	v_mfma_f32_16x16x32_bf16 v[122:125], v[162:165], v[186:189], v[122:125]
	v_mfma_f32_16x16x32_bf16 v[110:113], v[154:157], v[194:197], v[110:113]
	v_mfma_f32_16x16x32_bf16 v[106:109], v[162:165], v[194:197], v[106:109]
	v_mfma_f32_16x16x32_bf16 v[94:97], v[154:157], v[202:205], v[94:97]
	v_mfma_f32_16x16x32_bf16 v[90:93], v[162:165], v[202:205], v[90:93]
	v_mfma_f32_16x16x32_bf16 v[78:81], v[154:157], v[216:219], v[78:81]
	v_mfma_f32_16x16x32_bf16 v[74:77], v[162:165], v[216:219], v[74:77]
	s_setprio 0
	s_setprio 1
	v_mfma_f32_16x16x32_bf16 v[118:121], v[166:169], v[182:185], v[118:121]
	v_mfma_f32_16x16x32_bf16 v[114:117], v[174:177], v[182:185], v[114:117]
	v_mfma_f32_16x16x32_bf16 v[102:105], v[166:169], v[190:193], v[102:105]
	v_mfma_f32_16x16x32_bf16 v[98:101], v[174:177], v[190:193], v[98:101]
	v_mfma_f32_16x16x32_bf16 v[86:89], v[166:169], v[198:201], v[86:89]
	v_mfma_f32_16x16x32_bf16 v[82:85], v[174:177], v[198:201], v[82:85]
	v_mfma_f32_16x16x32_bf16 v[70:73], v[166:169], v[212:215], v[70:73]
	v_mfma_f32_16x16x32_bf16 v[66:69], v[174:177], v[212:215], v[66:69]
	v_mfma_f32_16x16x32_bf16 v[118:121], v[170:173], v[186:189], v[118:121]
	v_mfma_f32_16x16x32_bf16 v[114:117], v[178:181], v[186:189], v[114:117]
	v_mfma_f32_16x16x32_bf16 v[102:105], v[170:173], v[194:197], v[102:105]
	v_mfma_f32_16x16x32_bf16 v[98:101], v[178:181], v[194:197], v[98:101]
	v_mfma_f32_16x16x32_bf16 v[86:89], v[170:173], v[202:205], v[86:89]
	v_mfma_f32_16x16x32_bf16 v[82:85], v[178:181], v[202:205], v[82:85]
	v_mfma_f32_16x16x32_bf16 v[70:73], v[170:173], v[216:219], v[70:73]
	v_mfma_f32_16x16x32_bf16 v[66:69], v[178:181], v[216:219], v[66:69]
	s_setprio 0
	s_barrier
	s_add_i32 s89, s89, s26
	v_lshl_add_u64 v[208:209], s[78:79], 0, v[132:133]
	s_mov_b32 m0, s89
	ds_read_b128 v[182:185], v152 offset:16384
	ds_read_b128 v[186:189], v152 offset:17408
	ds_read_b128 v[190:193], v152 offset:18432
	ds_read_b128 v[194:197], v152 offset:19456
	ds_read_b128 v[198:201], v152 offset:20480
	ds_read_b128 v[202:205], v152 offset:21504
	ds_read_b128 v[212:215], v152 offset:22528
	ds_read_b128 v[216:219], v152 offset:23552
	global_load_lds_dwordx4 v[208:209], off
	s_add_i32 m0, s89, 0x2000
	s_add_u32 s90, s78, 0x40000
	v_lshl_add_u64 v[210:211], s[78:79], 0, v[136:137]
	s_addc_u32 s91, s79, 0
	s_add_i32 s89, s92, s26
	global_load_lds_dwordx4 v[210:211], off
	v_lshl_add_u64 v[220:221], s[90:91], 0, v[132:133]
	s_mov_b32 m0, s89
	v_lshl_add_u64 v[222:223], s[80:81], 0, v[134:135]
	global_load_lds_dwordx4 v[220:221], off
	s_add_i32 m0, s89, 0x2000
	v_lshl_add_u64 v[220:221], s[90:91], 0, v[136:137]
	global_load_lds_dwordx4 v[220:221], off
	s_mov_b32 m0, s7
	v_lshl_add_u64 v[220:221], s[80:81], 0, v[130:131]
	global_load_lds_dwordx4 v[220:221], off
	s_mov_b32 m0, s27
	s_nop 0
	global_load_lds_dwordx4 v[222:223], off
	s_waitcnt vmcnt(8)
	s_waitcnt lgkmcnt(0)
	s_barrier
; #define PG8_STAGE(bufoff, gbase, voff) do { _Pragma("unroll") for (int _i = 0; _i < 2; ++_i) \
;         __builtin_amdgcn_global_load_lds((const unsigned*)((const char*)(gbase) + (voff)[_i]), (PG8_LAS unsigned*)(lds + (bufoff) + ldsw + _i * 8192), 16, 0, 0); } while (0)
; #define PG8_LDA(dst, b, h) do { _Pragma("unroll") for (int m = 0; m < 4; ++m) _Pragma("unroll") for (int k = 0; k < 2; ++k) dst[m][k] = *(const PG8_LAS bf16x8*)(lds + PG8_SA(b, h) + aoff + m * 2048 + k * 1024); } while (0)
; #define PG8_LDB(dst, b, h) do { _Pragma("unroll") for (int n = 0; n < 2; ++n) _Pragma("unroll") for (int k = 0; k < 2; ++k) dst[n][k] = *(const PG8_LAS bf16x8*)(lds + PG8_SB(b, h) + boff + n * 2048 + k * 1024); } while (0)
; #define PG8_MMA(ai, bj, At, Bt) do { __builtin_amdgcn_s_setprio(1); _Pragma("unroll") for (int m = 0; m < 4; ++m) _Pragma("unroll") for (int n = 0; n < 2; ++n) _Pragma("unroll") for (int k = 0; k < 2; ++k) \
;         acc[ai][bj][m][n] = __builtin_amdgcn_mfma_f32_16x16x32_bf16(Bt[n][k], At[m][k], acc[ai][bj][m][n], 0, 0, 0); __builtin_amdgcn_s_setprio(0); } while (0)
; #define PG8_WAIT_V(n) asm volatile("s_waitcnt vmcnt(" #n ")" ::: "memory")
; #define PG8_WAIT_L(n) asm volatile("s_waitcnt lgkmcnt(" #n ")" ::: "memory")
; #define PG8_BAR __builtin_amdgcn_s_barrier()
; #define PG8_SCHED __builtin_amdgcn_sched_barrier(0)
; template <class Epi, class Sched, bool ALIGN_EPI = false, bool SP2 = false>
; __device__ __forceinline__ void gemm_phase(PG8_LAS unsigned char* lds, const Gemm g, const Sched& S, const Epi& E) {
;     ...
;             PG8_WAIT_V(8); PG8_WAIT_L(0); PG8_BAR; PG8_MMA(1, 0, At, B0); PG8_MMA(1, 1, At, B1); PG8_BAR; PG8_SCHED;
;             PG8_LDB(B0, 1, 0); PG8_LDB(B1, 1, 1); PG8_SCHED; PG8_LDA(At, 1, 0); PG8_STAGE(PG8_SA(0, 1), a2 + hstep, voffA);
;             PG8_WAIT_V(8); PG8_WAIT_L(0); PG8_BAR; PG8_MMA(0, 0, At, B0); PG8_MMA(0, 1, At, B1); PG8_BAR; PG8_SCHED;
	s_setprio 1
	s_waitcnt lgkmcnt(0)
	v_mfma_f32_16x16x32_bf16 v[62:65], v[142:145], v[182:185], v[62:65]
	v_mfma_f32_16x16x32_bf16 v[58:61], v[158:161], v[182:185], v[58:61]
	v_mfma_f32_16x16x32_bf16 v[46:49], v[142:145], v[190:193], v[46:49]
	v_mfma_f32_16x16x32_bf16 v[42:45], v[158:161], v[190:193], v[42:45]
	v_mfma_f32_16x16x32_bf16 v[30:33], v[142:145], v[198:201], v[30:33]
	v_mfma_f32_16x16x32_bf16 v[26:29], v[158:161], v[198:201], v[26:29]
	v_mfma_f32_16x16x32_bf16 v[14:17], v[142:145], v[212:215], v[14:17]
	v_mfma_f32_16x16x32_bf16 v[10:13], v[158:161], v[212:215], v[10:13]
	v_mfma_f32_16x16x32_bf16 v[62:65], v[154:157], v[186:189], v[62:65]
	v_mfma_f32_16x16x32_bf16 v[58:61], v[162:165], v[186:189], v[58:61]
	v_mfma_f32_16x16x32_bf16 v[46:49], v[154:157], v[194:197], v[46:49]
	v_mfma_f32_16x16x32_bf16 v[42:45], v[162:165], v[194:197], v[42:45]
	v_mfma_f32_16x16x32_bf16 v[30:33], v[154:157], v[202:205], v[30:33]
	v_mfma_f32_16x16x32_bf16 v[26:29], v[162:165], v[202:205], v[26:29]
	v_mfma_f32_16x16x32_bf16 v[14:17], v[154:157], v[216:219], v[14:17]
	v_mfma_f32_16x16x32_bf16 v[10:13], v[162:165], v[216:219], v[10:13]
	s_setprio 0
	s_setprio 1
	v_mfma_f32_16x16x32_bf16 v[54:57], v[166:169], v[182:185], v[54:57]
	v_mfma_f32_16x16x32_bf16 v[50:53], v[174:177], v[182:185], v[50:53]
	v_mfma_f32_16x16x32_bf16 v[38:41], v[166:169], v[190:193], v[38:41]
	v_mfma_f32_16x16x32_bf16 v[34:37], v[174:177], v[190:193], v[34:37]
	v_mfma_f32_16x16x32_bf16 v[22:25], v[166:169], v[198:201], v[22:25]
	v_mfma_f32_16x16x32_bf16 v[18:21], v[174:177], v[198:201], v[18:21]
	v_mfma_f32_16x16x32_bf16 v[6:9], v[166:169], v[212:215], v[6:9]
	v_mfma_f32_16x16x32_bf16 v[2:5], v[174:177], v[212:215], v[2:5]
	v_mfma_f32_16x16x32_bf16 v[54:57], v[170:173], v[186:189], v[54:57]
	v_mfma_f32_16x16x32_bf16 v[50:53], v[178:181], v[186:189], v[50:53]
	v_mfma_f32_16x16x32_bf16 v[38:41], v[170:173], v[194:197], v[38:41]
	v_mfma_f32_16x16x32_bf16 v[34:37], v[178:181], v[194:197], v[34:37]
	v_mfma_f32_16x16x32_bf16 v[22:25], v[170:173], v[202:205], v[22:25]
	v_mfma_f32_16x16x32_bf16 v[18:21], v[178:181], v[202:205], v[18:21]
	v_mfma_f32_16x16x32_bf16 v[6:9], v[170:173], v[216:219], v[6:9]
	v_mfma_f32_16x16x32_bf16 v[2:5], v[178:181], v[216:219], v[2:5]
	s_setprio 0
	s_barrier
	s_add_i32 s89, 0, 0x18000
	v_add_u32_e32 v0, s89, v149
	s_add_i32 s90, 0, 0x1c000
	ds_read_b128 v[142:145], v0
	ds_read_b128 v[154:157], v0 offset:1024
	ds_read_b128 v[158:161], v0 offset:2048
	ds_read_b128 v[162:165], v0 offset:3072
	v_add_u32_e32 v0, s90, v149
	ds_read_b128 v[166:169], v0
	ds_read_b128 v[170:173], v0 offset:1024
	ds_read_b128 v[174:177], v0 offset:2048
	ds_read_b128 v[178:181], v0 offset:3072
	s_add_u32 s80, s80, 0x40000
	s_addc_u32 s81, s81, 0
	s_mov_b32 m0, s28
	v_lshl_add_u64 v[224:225], s[80:81], 0, v[130:131]
	ds_read_b128 v[182:185], v152 offset:32768
	ds_read_b128 v[186:189], v152 offset:33792
	ds_read_b128 v[190:193], v152 offset:34816
	ds_read_b128 v[194:197], v152 offset:35840
	ds_read_b128 v[198:201], v152 offset:36864
	ds_read_b128 v[202:205], v152 offset:37888
	ds_read_b128 v[212:215], v152 offset:38912
	ds_read_b128 v[216:219], v152 offset:39936
	global_load_lds_dwordx4 v[224:225], off
	s_mov_b32 m0, s29
	v_lshl_add_u64 v[224:225], s[80:81], 0, v[134:135]
	global_load_lds_dwordx4 v[224:225], off
	s_waitcnt vmcnt(8)
	s_waitcnt lgkmcnt(0)
	s_barrier
	s_setprio 1
	s_waitcnt lgkmcnt(0)
	v_mfma_f32_16x16x32_bf16 v[126:129], v[142:145], v[182:185], v[126:129]
	v_mfma_f32_16x16x32_bf16 v[122:125], v[158:161], v[182:185], v[122:125]
	v_mfma_f32_16x16x32_bf16 v[110:113], v[142:145], v[190:193], v[110:113]
	v_mfma_f32_16x16x32_bf16 v[106:109], v[158:161], v[190:193], v[106:109]
	v_mfma_f32_16x16x32_bf16 v[94:97], v[142:145], v[198:201], v[94:97]
	v_mfma_f32_16x16x32_bf16 v[90:93], v[158:161], v[198:201], v[90:93]
	v_mfma_f32_16x16x32_bf16 v[78:81], v[142:145], v[212:215], v[78:81]
	v_mfma_f32_16x16x32_bf16 v[74:77], v[158:161], v[212:215], v[74:77]
	v_mfma_f32_16x16x32_bf16 v[126:129], v[154:157], v[186:189], v[126:129]
	v_mfma_f32_16x16x32_bf16 v[122:125], v[162:165], v[186:189], v[122:125]
	v_mfma_f32_16x16x32_bf16 v[110:113], v[154:157], v[194:197], v[110:113]
	v_mfma_f32_16x16x32_bf16 v[106:109], v[162:165], v[194:197], v[106:109]
	v_mfma_f32_16x16x32_bf16 v[94:97], v[154:157], v[202:205], v[94:97]
	v_mfma_f32_16x16x32_bf16 v[90:93], v[162:165], v[202:205], v[90:93]
	v_mfma_f32_16x16x32_bf16 v[78:81], v[154:157], v[216:219], v[78:81]
	v_mfma_f32_16x16x32_bf16 v[74:77], v[162:165], v[216:219], v[74:77]
	s_setprio 0
	s_setprio 1
	v_mfma_f32_16x16x32_bf16 v[118:121], v[166:169], v[182:185], v[118:121]
	v_mfma_f32_16x16x32_bf16 v[114:117], v[174:177], v[182:185], v[114:117]
	v_mfma_f32_16x16x32_bf16 v[102:105], v[166:169], v[190:193], v[102:105]
	v_mfma_f32_16x16x32_bf16 v[98:101], v[174:177], v[190:193], v[98:101]
	v_mfma_f32_16x16x32_bf16 v[86:89], v[166:169], v[198:201], v[86:89]
	v_mfma_f32_16x16x32_bf16 v[82:85], v[174:177], v[198:201], v[82:85]
	v_mfma_f32_16x16x32_bf16 v[70:73], v[166:169], v[212:215], v[70:73]
	v_mfma_f32_16x16x32_bf16 v[66:69], v[174:177], v[212:215], v[66:69]
	v_mfma_f32_16x16x32_bf16 v[118:121], v[170:173], v[186:189], v[118:121]
	v_mfma_f32_16x16x32_bf16 v[114:117], v[178:181], v[186:189], v[114:117]
	v_mfma_f32_16x16x32_bf16 v[102:105], v[170:173], v[194:197], v[102:105]
	v_mfma_f32_16x16x32_bf16 v[98:101], v[178:181], v[194:197], v[98:101]
	v_mfma_f32_16x16x32_bf16 v[86:89], v[170:173], v[202:205], v[86:89]
	v_mfma_f32_16x16x32_bf16 v[82:85], v[178:181], v[202:205], v[82:85]
	v_mfma_f32_16x16x32_bf16 v[70:73], v[170:173], v[216:219], v[70:73]
	v_mfma_f32_16x16x32_bf16 v[66:69], v[178:181], v[216:219], v[66:69]
	s_setprio 0
	s_barrier
; #define PG8_STAGE(bufoff, gbase, voff) do { _Pragma("unroll") for (int _i = 0; _i < 2; ++_i) \
;         __builtin_amdgcn_global_load_lds((const unsigned*)((const char*)(gbase) + (voff)[_i]), (PG8_LAS unsigned*)(lds + (bufoff) + ldsw + _i * 8192), 16, 0, 0); } while (0)
; #define PG8_LDA(dst, b, h) do { _Pragma("unroll") for (int m = 0; m < 4; ++m) _Pragma("unroll") for (int k = 0; k < 2; ++k) dst[m][k] = *(const PG8_LAS bf16x8*)(lds + PG8_SA(b, h) + aoff + m * 2048 + k * 1024); } while (0)
; #define PG8_MMA(ai, bj, At, Bt) do { __builtin_amdgcn_s_setprio(1); _Pragma("unroll") for (int m = 0; m < 4; ++m) _Pragma("unroll") for (int n = 0; n < 2; ++n) _Pragma("unroll") for (int k = 0; k < 2; ++k) \
;         acc[ai][bj][m][n] = __builtin_amdgcn_mfma_f32_16x16x32_bf16(Bt[n][k], At[m][k], acc[ai][bj][m][n], 0, 0, 0); __builtin_amdgcn_s_setprio(0); } while (0)
; #define PG8_WAIT_V(n) asm volatile("s_waitcnt vmcnt(" #n ")" ::: "memory")
; #define PG8_WAIT_L(n) asm volatile("s_waitcnt lgkmcnt(" #n ")" ::: "memory")
; #define PG8_BAR __builtin_amdgcn_s_barrier()
; #define PG8_SCHED __builtin_amdgcn_sched_barrier(0)
; template <class Epi, class Sched, bool ALIGN_EPI = false, bool SP2 = false>
; __device__ __forceinline__ void gemm_phase(PG8_LAS unsigned char* lds, const Gemm g, const Sched& S, const Epi& E) {
;     ...
;             PG8_LDA(At, 1, 1); PG8_STAGE(PG8_SB(1, 0), b3, voffB); PG8_STAGE(PG8_SB(1, 1), b3 + hstep, voffB); PG8_STAGE(PG8_SA(1, 0), a3, voffA);
;             PG8_WAIT_V(8); PG8_WAIT_L(0); PG8_BAR; PG8_MMA(1, 0, At, B0); PG8_MMA(1, 1, At, B1); PG8_BAR; PG8_SCHED;
	s_add_i32 s80, s89, s26
	v_lshl_add_u64 v[208:209], v[208:209], 0, s[24:25]
	s_mov_b32 m0, s80
	ds_read_b128 v[182:185], v152 offset:49152
	ds_read_b128 v[186:189], v152 offset:50176
	ds_read_b128 v[190:193], v152 offset:51200
	ds_read_b128 v[194:197], v152 offset:52224
	ds_read_b128 v[198:201], v152 offset:53248
	ds_read_b128 v[202:205], v152 offset:54272
	ds_read_b128 v[212:215], v152 offset:55296
	ds_read_b128 v[216:219], v152 offset:56320
	global_load_lds_dwordx4 v[208:209], off
	s_add_i32 m0, s80, 0x2000
	s_add_u32 s78, s78, 0x40080
	v_lshl_add_u64 v[208:209], v[210:211], 0, s[24:25]
	s_addc_u32 s79, s79, 0
	s_add_i32 s80, s90, s26
	global_load_lds_dwordx4 v[208:209], off
	s_mov_b32 m0, s80
	v_lshl_add_u64 v[208:209], s[78:79], 0, v[132:133]
	global_load_lds_dwordx4 v[208:209], off
	s_add_i32 m0, s80, 0x2000
	v_lshl_add_u64 v[208:209], s[78:79], 0, v[136:137]
	global_load_lds_dwordx4 v[208:209], off
	s_mov_b32 m0, s43
	v_lshl_add_u64 v[208:209], v[220:221], 0, s[24:25]
	global_load_lds_dwordx4 v[208:209], off
	s_mov_b32 m0, s44
	v_lshl_add_u64 v[208:209], v[222:223], 0, s[24:25]
	global_load_lds_dwordx4 v[208:209], off
	s_waitcnt vmcnt(8)
	s_waitcnt lgkmcnt(0)
	s_barrier
	s_setprio 1
	s_waitcnt lgkmcnt(0)
	v_mfma_f32_16x16x32_bf16 v[62:65], v[142:145], v[182:185], v[62:65]
	v_mfma_f32_16x16x32_bf16 v[58:61], v[158:161], v[182:185], v[58:61]
	v_mfma_f32_16x16x32_bf16 v[46:49], v[142:145], v[190:193], v[46:49]
	v_mfma_f32_16x16x32_bf16 v[42:45], v[158:161], v[190:193], v[42:45]
	v_mfma_f32_16x16x32_bf16 v[30:33], v[142:145], v[198:201], v[30:33]
	v_mfma_f32_16x16x32_bf16 v[26:29], v[158:161], v[198:201], v[26:29]
	v_mfma_f32_16x16x32_bf16 v[14:17], v[142:145], v[212:215], v[14:17]
	v_mfma_f32_16x16x32_bf16 v[10:13], v[158:161], v[212:215], v[10:13]
	v_mfma_f32_16x16x32_bf16 v[62:65], v[154:157], v[186:189], v[62:65]
	v_mfma_f32_16x16x32_bf16 v[58:61], v[162:165], v[186:189], v[58:61]
	v_mfma_f32_16x16x32_bf16 v[46:49], v[154:157], v[194:197], v[46:49]
	v_mfma_f32_16x16x32_bf16 v[42:45], v[162:165], v[194:197], v[42:45]
	v_mfma_f32_16x16x32_bf16 v[30:33], v[154:157], v[202:205], v[30:33]
	v_mfma_f32_16x16x32_bf16 v[26:29], v[162:165], v[202:205], v[26:29]
	v_mfma_f32_16x16x32_bf16 v[14:17], v[154:157], v[216:219], v[14:17]
	v_mfma_f32_16x16x32_bf16 v[10:13], v[162:165], v[216:219], v[10:13]
	s_setprio 0
	s_setprio 1
	v_mfma_f32_16x16x32_bf16 v[54:57], v[166:169], v[182:185], v[54:57]
	v_mfma_f32_16x16x32_bf16 v[50:53], v[174:177], v[182:185], v[50:53]
	v_mfma_f32_16x16x32_bf16 v[38:41], v[166:169], v[190:193], v[38:41]
	v_mfma_f32_16x16x32_bf16 v[34:37], v[174:177], v[190:193], v[34:37]
	v_mfma_f32_16x16x32_bf16 v[22:25], v[166:169], v[198:201], v[22:25]
	v_mfma_f32_16x16x32_bf16 v[18:21], v[174:177], v[198:201], v[18:21]
	v_mfma_f32_16x16x32_bf16 v[6:9], v[166:169], v[212:215], v[6:9]
	v_mfma_f32_16x16x32_bf16 v[2:5], v[174:177], v[212:215], v[2:5]
	v_mfma_f32_16x16x32_bf16 v[54:57], v[170:173], v[186:189], v[54:57]
	v_mfma_f32_16x16x32_bf16 v[50:53], v[178:181], v[186:189], v[50:53]
	v_mfma_f32_16x16x32_bf16 v[38:41], v[170:173], v[194:197], v[38:41]
	v_mfma_f32_16x16x32_bf16 v[34:37], v[178:181], v[194:197], v[34:37]
	v_mfma_f32_16x16x32_bf16 v[22:25], v[170:173], v[202:205], v[22:25]
	v_mfma_f32_16x16x32_bf16 v[18:21], v[178:181], v[202:205], v[18:21]
	v_mfma_f32_16x16x32_bf16 v[6:9], v[170:173], v[216:219], v[6:9]
	v_mfma_f32_16x16x32_bf16 v[2:5], v[178:181], v[216:219], v[2:5]
	s_setprio 0
	s_barrier
	s_add_i32 s88, s88, 2
	s_add_u32 s76, s76, 0x100
	s_addc_u32 s77, s77, 0
	s_add_u32 s84, s84, 0x100
	s_addc_u32 s85, s85, 0
	s_cmp_gt_u32 s88, 13
	s_cbranch_scc0 .LBB0_509
	s_and_b64 vcc, exec, s[64:65]
	s_cbranch_vccz .LBB0_546
	s_barrier
	v_lshl_add_u32 v142, s6, 8, v148
	s_cmp_ge_i32 s74, s42
	s_mov_b64 s[76:77], -1
	s_cbranch_scc1 .LBB0_547
